# mixer y stores: pairs of row-per-lane dwordx2 stores merged into dwordx4 via v_permlane32_swap (4 store_head sites), vmcnt waits re-derived; nop-padded kernel ends
# speedup vs baseline: 1.0109x; 1.0109x over previous
; DI unsigned pk_bf16(float lo, float hi) { f32x2 v = {lo, hi}; bf2_t b = __builtin_convertvector(v, bf2_t); return __builtin_bit_cast(unsigned, b); }
; DI float bf_lo(unsigned u) { return __uint_as_float(u << 16); }
; DI float bf_hi(unsigned u) { return __uint_as_float(u & 0xffff0000u); }
; DI float silu(float x) { return x * __builtin_amdgcn_rcpf(1.0f + __builtin_amdgcn_exp2f(-1.4426950408889634f * x)); }
; DI void store_head(const f32x16& o0, const f32x16& o1, float rs, const unsigned char* gl, int tr, int ch0, const float* gs, bf16_t* yp) {
;     u32x2 gt[8]; f32x4 gv[8];
; #pragma unroll
;     for (int q = 0; q < 8; ++q) { const int d = 32 * (q >> 2) + 8 * (q & 3); gt[q] = *(const u32x2*)(gl + gate_off(tr, ch0 + d)); gv[q] = *(const f32x4*)(gs + d); }
; #pragma unroll
;     for (int q = 0; q < 8; ++q) { const int d = 32 * (q >> 2) + 8 * (q & 3), g = q & 3;
;         const f32x16& o = (q >> 2) ? o1 : o0;
;         u32x2 w; w.x = pk_bf16(o[4 * g + 0] * rs * gv[q][0] * silu(bf_lo(gt[q].x)), o[4 * g + 1] * rs * gv[q][1] * silu(bf_hi(gt[q].x)));
;         w.y = pk_bf16(o[4 * g + 2] * rs * gv[q][2] * silu(bf_lo(gt[q].y)), o[4 * g + 3] * rs * gv[q][3] * silu(bf_hi(gt[q].y)));
;         *(u32x2*)(yp + d) = w; }
; }
; DI void mixer_phase(const Params& p, unsigned char* ldsraw, int vid) {
;     ...
;             __syncthreads();
;             float totA = 0.f, totB = 0.f;
; #pragma unroll
;             for (int w8 = 0; w8 < 8; ++w8) { totA += lf[w8 * 32 + r]; totB += lf[256 + w8 * 32 + r]; }
;             const float* gs = p.g_sb + 64 * wid + 4 * hh;
;             store_head(oA0, oA1, rsqrtf(totA * (1.0f / 512.0f) + EPS), gl, r, 64 * wid + 4 * hh, gs, Y + (size_t)tqA * 1024 + 64 * wid + 4 * hh);
;             store_head(oB0, oB1, rsqrtf(totB * (1.0f / 512.0f) + EPS), gl, r + 32, 64 * wid + 4 * hh, gs, Y + (size_t)tqB * 1024 + 64 * wid + 4 * hh);
.LBB0_414:
	s_or_b64 exec, exec, s[0:1]
	v_lshlrev_b32_e32 v144, 2, v176
	v_add_u32_e32 v158, s74, v144
	v_add_u32_e32 v70, 16, v158
	v_and_b32_e32 v160, 15, v205
	v_lshlrev_b32_e32 v71, 1, v70
	v_lshrrev_b32_e32 v70, 3, v70
	v_or_b32_e32 v96, s38, v206
	v_lshl_add_u32 v161, v206, 2, 0
	v_bitop3_b32 v70, v70, v160, 63 bitop3:0x6c
	v_add_u32_e32 v64, 0x400, v161
	v_ashrrev_i32_e32 v97, 31, v96
	v_and_b32_e32 v72, 0xfffffc00, v71
	v_lshlrev_b32_e32 v70, 4, v70
	v_and_b32_e32 v138, 8, v71
	v_add_u32_e32 v71, 24, v158
	s_waitcnt vmcnt(0)
	s_waitcnt lgkmcnt(0)
	s_barrier
	ds_read2_b32 v[102:103], v161 offset1:32
	ds_read2_b32 v[110:111], v64 offset1:32
	ds_read2_b32 v[108:109], v161 offset0:64 offset1:96
	ds_read2_b32 v[112:113], v64 offset0:64 offset1:96
	ds_read2_b32 v[106:107], v161 offset0:128 offset1:160
	ds_read2_b32 v[114:115], v64 offset0:128 offset1:160
	ds_read2_b32 v[104:105], v161 offset0:192 offset1:224
	ds_read2_b32 v[116:117], v64 offset0:192 offset1:224
	v_ashrrev_i32_e32 v145, 31, v144
	v_lshlrev_b64 v[64:65], 11, v[96:97]
	v_add3_u32 v139, 0, v70, v72
	v_lshlrev_b32_e32 v72, 1, v71
	v_lshrrev_b32_e32 v71, 3, v71
	v_lshl_add_u64 v[64:65], s[80:81], 0, v[64:65]
	v_lshlrev_b64 v[100:101], 1, v[144:145]
	v_lshrrev_b32_e32 v66, 3, v158
	v_bitop3_b32 v71, v71, v160, 63 bitop3:0x6c
	v_lshl_add_u64 v[140:141], v[64:65], 0, v[100:101]
	v_lshlrev_b32_e32 v64, 1, v158
	v_bitop3_b32 v66, v66, v160, 63 bitop3:0x6c
	v_and_b32_e32 v73, 0xfffffc00, v72
	v_lshlrev_b32_e32 v71, 4, v71
	v_and_b32_e32 v146, 8, v72
	v_add_u32_e32 v72, 32, v158
	v_and_b32_e32 v65, 0xfffffc00, v64
	v_lshlrev_b32_e32 v66, 4, v66
	v_and_b32_e32 v134, 8, v64
	v_add_u32_e32 v64, 8, v158
	v_add3_u32 v147, 0, v71, v73
	v_lshlrev_b32_e32 v73, 1, v72
	v_lshrrev_b32_e32 v72, 3, v72
	v_add_u32_e32 v90, 48, v158
	v_add3_u32 v135, 0, v66, v65
	v_lshlrev_b32_e32 v65, 1, v64
	v_lshrrev_b32_e32 v64, 3, v64
	v_bitop3_b32 v72, v72, v160, 63 bitop3:0x6c
	v_lshlrev_b32_e32 v91, 1, v90
	v_lshrrev_b32_e32 v90, 3, v90
	v_bitop3_b32 v64, v64, v160, 63 bitop3:0x6c
	v_and_b32_e32 v74, 0xfffffc00, v73
	v_lshlrev_b32_e32 v72, 4, v72
	v_bitop3_b32 v90, v90, v160, 63 bitop3:0x6c
	v_lshlrev_b32_e32 v159, 11, v206
	v_and_b32_e32 v66, 0xfffffc00, v65
	v_lshlrev_b32_e32 v64, 4, v64
	v_add3_u32 v149, 0, v72, v74
	v_add_u32_e32 v72, 40, v158
	v_and_b32_e32 v92, 0xfffffc00, v91
	v_lshlrev_b32_e32 v90, 4, v90
	v_and_b32_e32 v152, 8, v91
	v_add_u32_e32 v91, 56, v158
	v_lshl_add_u64 v[98:99], v[144:145], 2, s[56:57]
	v_add3_u32 v68, v135, v159, v134
	v_and_b32_e32 v136, 8, v65
	v_add3_u32 v137, 0, v64, v66
	v_and_b32_e32 v148, 8, v73
	v_lshlrev_b32_e32 v73, 1, v72
	v_lshrrev_b32_e32 v72, 3, v72
	v_add3_u32 v153, 0, v90, v92
	v_lshlrev_b32_e32 v92, 1, v91
	v_lshrrev_b32_e32 v91, 3, v91
	v_add3_u32 v69, v137, v159, v136
	global_load_dwordx4 v[76:79], v[98:99], off
	global_load_dwordx4 v[64:67], v[98:99], off offset:32
	v_add3_u32 v70, v139, v159, v138
	v_add3_u32 v71, v147, v159, v146
	ds_read_b64 v[118:119], v68 offset:4096
	ds_read_b64 v[124:125], v69 offset:4096
	ds_read_b64 v[128:129], v70 offset:4096
	ds_read_b64 v[142:143], v71 offset:4096
	v_bitop3_b32 v72, v72, v160, 63 bitop3:0x6c
	v_bitop3_b32 v91, v91, v160, 63 bitop3:0x6c
	v_and_b32_e32 v74, 0xfffffc00, v73
	v_lshlrev_b32_e32 v72, 4, v72
	v_and_b32_e32 v93, 0xfffffc00, v92
	v_lshlrev_b32_e32 v91, 4, v91
	v_add3_u32 v88, v149, v159, v148
	v_and_b32_e32 v150, 8, v73
	v_add3_u32 v151, 0, v72, v74
	v_and_b32_e32 v154, 8, v92
	v_add3_u32 v155, 0, v91, v93
	s_waitcnt lgkmcnt(3)
	v_lshlrev_b32_e32 v120, 16, v118
	global_load_dwordx4 v[80:83], v[98:99], off offset:64
	global_load_dwordx4 v[68:71], v[98:99], off offset:96
	v_add3_u32 v89, v151, v159, v150
	global_load_dwordx4 v[84:87], v[98:99], off offset:128
	global_load_dwordx4 v[72:75], v[98:99], off offset:160
	v_add3_u32 v90, v153, v159, v152
	v_add3_u32 v91, v155, v159, v154
	ds_read_b64 v[156:157], v88 offset:4096
	ds_read_b64 v[162:163], v89 offset:4096
	ds_read_b64 v[130:131], v90 offset:4096
	ds_read_b64 v[122:123], v91 offset:4096
	v_and_b32_e32 v121, 0xffff0000, v118
	v_mul_f32_e32 v88, 0xbfb8aa3b, v120
	v_exp_f32_e32 v118, v88
	v_mul_f32_e32 v88, 0xbfb8aa3b, v121
	v_exp_f32_e32 v127, v88
	v_lshlrev_b32_e32 v132, 16, v119
	v_add_f32_e32 v118, 1.0, v118
	v_rcp_f32_e32 v126, v118
	v_add_f32_e32 v118, 1.0, v127
	v_rcp_f32_e32 v127, v118
	v_and_b32_e32 v133, 0xffff0000, v119
	v_mul_f32_e32 v118, 0xbfb8aa3b, v132
	v_exp_f32_e32 v164, v118
	v_mul_f32_e32 v118, 0xbfb8aa3b, v133
	v_exp_f32_e32 v165, v118
	v_pk_mul_f32 v[118:119], v[126:127], v[120:121]
	s_waitcnt lgkmcnt(6)
	v_lshlrev_b32_e32 v126, 16, v124
	v_and_b32_e32 v127, 0xffff0000, v124
	v_mul_f32_e32 v124, 0xbfb8aa3b, v126
	v_add_f32_e32 v120, 1.0, v164
	v_add_f32_e32 v121, 1.0, v165
	v_exp_f32_e32 v124, v124
	v_mul_f32_e32 v164, 0xbfb8aa3b, v127
	v_rcp_f32_e32 v120, v120
	v_rcp_f32_e32 v121, v121
	v_exp_f32_e32 v164, v164
	v_add_f32_e32 v124, 1.0, v124
	v_and_b32_e32 v165, 0xffff0000, v125
	v_pk_mul_f32 v[120:121], v[120:121], v[132:133]
	v_rcp_f32_e32 v132, v124
	v_add_f32_e32 v124, 1.0, v164
	v_lshlrev_b32_e32 v164, 16, v125
	v_rcp_f32_e32 v133, v124
	v_mul_f32_e32 v124, 0xbfb8aa3b, v164
	v_exp_f32_e32 v166, v124
	v_mul_f32_e32 v124, 0xbfb8aa3b, v165
	global_load_dwordx4 v[92:95], v[98:99], off offset:192
	global_load_dwordx4 v[88:91], v[98:99], off offset:224
	v_exp_f32_e32 v167, v124
	v_pk_mul_f32 v[124:125], v[132:133], v[126:127]
	s_waitcnt lgkmcnt(5)
; DI unsigned pk_bf16(float lo, float hi) { f32x2 v = {lo, hi}; bf2_t b = __builtin_convertvector(v, bf2_t); return __builtin_bit_cast(unsigned, b); }
; DI float bf_lo(unsigned u) { return __uint_as_float(u << 16); }
; DI float bf_hi(unsigned u) { return __uint_as_float(u & 0xffff0000u); }
; DI float silu(float x) { return x * __builtin_amdgcn_rcpf(1.0f + __builtin_amdgcn_exp2f(-1.4426950408889634f * x)); }
; DI void store_head(const f32x16& o0, const f32x16& o1, float rs, const unsigned char* gl, int tr, int ch0, const float* gs, bf16_t* yp) {
;     u32x2 gt[8]; f32x4 gv[8];
; #pragma unroll
;     for (int q = 0; q < 8; ++q) { const int d = 32 * (q >> 2) + 8 * (q & 3); gt[q] = *(const u32x2*)(gl + gate_off(tr, ch0 + d)); gv[q] = *(const f32x4*)(gs + d); }
; #pragma unroll
;     for (int q = 0; q < 8; ++q) { const int d = 32 * (q >> 2) + 8 * (q & 3), g = q & 3;
;         const f32x16& o = (q >> 2) ? o1 : o0;
;         u32x2 w; w.x = pk_bf16(o[4 * g + 0] * rs * gv[q][0] * silu(bf_lo(gt[q].x)), o[4 * g + 1] * rs * gv[q][1] * silu(bf_hi(gt[q].x)));
;         w.y = pk_bf16(o[4 * g + 2] * rs * gv[q][2] * silu(bf_lo(gt[q].y)), o[4 * g + 3] * rs * gv[q][3] * silu(bf_hi(gt[q].y)));
; DI void mixer_phase(const Params& p, unsigned char* ldsraw, int vid) {
;     ...
;             float totA = 0.f, totB = 0.f;
; #pragma unroll
;             for (int w8 = 0; w8 < 8; ++w8) { totA += lf[w8 * 32 + r]; totB += lf[256 + w8 * 32 + r]; }
;             const float* gs = p.g_sb + 64 * wid + 4 * hh;
;             store_head(oA0, oA1, rsqrtf(totA * (1.0f / 512.0f) + EPS), gl, r, 64 * wid + 4 * hh, gs, Y + (size_t)tqA * 1024 + 64 * wid + 4 * hh);
	v_lshlrev_b32_e32 v132, 16, v128
	v_and_b32_e32 v133, 0xffff0000, v128
	v_mul_f32_e32 v128, 0xbfb8aa3b, v132
	v_add_f32_e32 v126, 1.0, v166
	v_add_f32_e32 v127, 1.0, v167
	v_exp_f32_e32 v128, v128
	v_mul_f32_e32 v166, 0xbfb8aa3b, v133
	v_rcp_f32_e32 v126, v126
	v_rcp_f32_e32 v127, v127
	v_exp_f32_e32 v166, v166
	v_add_f32_e32 v128, 1.0, v128
	v_and_b32_e32 v167, 0xffff0000, v129
	v_pk_mul_f32 v[126:127], v[126:127], v[164:165]
	v_rcp_f32_e32 v164, v128
	v_add_f32_e32 v128, 1.0, v166
	v_lshlrev_b32_e32 v166, 16, v129
	v_rcp_f32_e32 v165, v128
	v_mul_f32_e32 v128, 0xbfb8aa3b, v166
	v_exp_f32_e32 v168, v128
	v_mul_f32_e32 v128, 0xbfb8aa3b, v167
	v_exp_f32_e32 v169, v128
	v_pk_mul_f32 v[128:129], v[164:165], v[132:133]
	s_waitcnt lgkmcnt(4)
	v_lshlrev_b32_e32 v164, 16, v142
	v_and_b32_e32 v165, 0xffff0000, v142
	v_mul_f32_e32 v142, 0xbfb8aa3b, v164
	v_add_f32_e32 v132, 1.0, v168
	v_add_f32_e32 v133, 1.0, v169
	v_exp_f32_e32 v142, v142
	v_mul_f32_e32 v168, 0xbfb8aa3b, v165
	v_rcp_f32_e32 v132, v132
	v_rcp_f32_e32 v133, v133
	v_exp_f32_e32 v168, v168
	v_add_f32_e32 v142, 1.0, v142
	v_mov_b32_e32 v188, v110
	v_pk_mul_f32 v[132:133], v[132:133], v[166:167]
	v_rcp_f32_e32 v166, v142
	v_add_f32_e32 v142, 1.0, v168
	v_rcp_f32_e32 v167, v142
	v_lshlrev_b32_e32 v142, 16, v143
	v_and_b32_e32 v143, 0xffff0000, v143
	v_mul_f32_e32 v168, 0xbfb8aa3b, v142
	v_exp_f32_e32 v168, v168
	v_mul_f32_e32 v169, 0xbfb8aa3b, v143
	v_exp_f32_e32 v169, v169
	v_pk_mul_f32 v[164:165], v[166:167], v[164:165]
	v_add_f32_e32 v166, 1.0, v168
	s_waitcnt lgkmcnt(3)
	v_lshlrev_b32_e32 v168, 16, v156
	v_add_f32_e32 v167, 1.0, v169
	v_and_b32_e32 v169, 0xffff0000, v156
	v_mul_f32_e32 v156, 0xbfb8aa3b, v168
	v_exp_f32_e32 v156, v156
	v_mul_f32_e32 v170, 0xbfb8aa3b, v169
	v_rcp_f32_e32 v166, v166
	v_rcp_f32_e32 v167, v167
	v_exp_f32_e32 v170, v170
	v_add_f32_e32 v156, 1.0, v156
	v_mov_b32_e32 v189, v102
	v_pk_mul_f32 v[142:143], v[166:167], v[142:143]
	v_rcp_f32_e32 v166, v156
	v_add_f32_e32 v156, 1.0, v170
	v_rcp_f32_e32 v167, v156
	v_lshlrev_b32_e32 v156, 16, v157
	v_and_b32_e32 v157, 0xffff0000, v157
	v_mul_f32_e32 v170, 0xbfb8aa3b, v156
	v_exp_f32_e32 v170, v170
	v_mul_f32_e32 v171, 0xbfb8aa3b, v157
	v_exp_f32_e32 v171, v171
	v_pk_mul_f32 v[166:167], v[166:167], v[168:169]
	v_add_f32_e32 v168, 1.0, v170
	s_waitcnt lgkmcnt(2)
	v_lshlrev_b32_e32 v170, 16, v162
	v_add_f32_e32 v169, 1.0, v171
	v_and_b32_e32 v171, 0xffff0000, v162
	v_mul_f32_e32 v162, 0xbfb8aa3b, v170
	v_exp_f32_e32 v162, v162
	v_mul_f32_e32 v172, 0xbfb8aa3b, v171
	v_rcp_f32_e32 v168, v168
	v_rcp_f32_e32 v169, v169
	v_exp_f32_e32 v172, v172
	v_add_f32_e32 v162, 1.0, v162
	v_pk_add_f32 v[188:189], v[188:189], 0 op_sel_hi:[1,0]
	v_pk_mul_f32 v[156:157], v[168:169], v[156:157]
	v_rcp_f32_e32 v168, v162
	v_add_f32_e32 v162, 1.0, v172
	v_rcp_f32_e32 v169, v162
	v_lshlrev_b32_e32 v162, 16, v163
	v_and_b32_e32 v163, 0xffff0000, v163
	v_mul_f32_e32 v172, 0xbfb8aa3b, v162
	v_exp_f32_e32 v172, v172
	v_mul_f32_e32 v173, 0xbfb8aa3b, v163
	v_exp_f32_e32 v173, v173
	v_mov_b32_e32 v102, v111
	v_pk_add_f32 v[102:103], v[188:189], v[102:103]
	v_mov_b32_e32 v110, v112
	v_mov_b32_e32 v111, v108
	v_pk_add_f32 v[102:103], v[102:103], v[110:111]
	v_mov_b32_e32 v108, v113
	v_pk_mul_f32 v[168:169], v[168:169], v[170:171]
	v_add_f32_e32 v170, 1.0, v172
	s_waitcnt lgkmcnt(1)
	v_lshlrev_b32_e32 v172, 16, v130
	v_pk_add_f32 v[102:103], v[102:103], v[108:109]
	v_mov_b32_e32 v108, v114
	v_mov_b32_e32 v109, v106
	v_add_f32_e32 v171, 1.0, v173
	v_and_b32_e32 v173, 0xffff0000, v130
	v_mul_f32_e32 v130, 0xbfb8aa3b, v172
	v_pk_add_f32 v[102:103], v[102:103], v[108:109]
	v_mov_b32_e32 v106, v115
	v_exp_f32_e32 v130, v130
	v_mul_f32_e32 v174, 0xbfb8aa3b, v173
	v_pk_add_f32 v[102:103], v[102:103], v[106:107]
	v_mov_b32_e32 v106, v116
	v_mov_b32_e32 v107, v104
	v_rcp_f32_e32 v170, v170
	v_rcp_f32_e32 v171, v171
	v_exp_f32_e32 v174, v174
	v_pk_add_f32 v[102:103], v[102:103], v[106:107]
	v_mov_b32_e32 v104, v117
	v_pk_add_f32 v[102:103], v[102:103], v[104:105]
	s_mov_b32 s0, 0x3b000000
	v_pk_fma_f32 v[102:103], v[102:103], s[0:1], v[178:179] op_sel_hi:[1,0,0]
	v_add_f32_e32 v130, 1.0, v130
	v_mul_f32_e32 v104, 0x4b800000, v103
	v_cmp_gt_f32_e32 vcc, s98, v103
	v_pk_mul_f32 v[162:163], v[170:171], v[162:163]
	v_rcp_f32_e32 v170, v130
	v_add_f32_e32 v130, 1.0, v174
	v_cndmask_b32_e32 v103, v103, v104, vcc
	v_rcp_f32_e32 v171, v130
	v_lshlrev_b32_e32 v130, 16, v131
	v_and_b32_e32 v131, 0xffff0000, v131
	v_rsq_f32_e32 v103, v103
	v_mul_f32_e32 v175, 0xbfb8aa3b, v131
	v_exp_f32_e32 v175, v175
	v_mul_f32_e32 v174, 0xbfb8aa3b, v130
	v_exp_f32_e32 v174, v174
	v_mul_f32_e32 v110, 0x45800000, v103
	v_cndmask_b32_e32 v110, v103, v110, vcc
	v_pk_mul_f32 v[170:171], v[170:171], v[172:173]
	v_add_f32_e32 v173, 1.0, v175
	s_waitcnt lgkmcnt(0)
	v_and_b32_e32 v175, 0xffff0000, v122
	v_pk_mul_f32 v[48:49], v[48:49], v[110:111] op_sel_hi:[1,0]
	v_pk_mul_f32 v[50:51], v[50:51], v[110:111] op_sel_hi:[1,0]
	v_pk_mul_f32 v[32:33], v[32:33], v[110:111] op_sel_hi:[1,0]
	v_pk_mul_f32 v[34:35], v[34:35], v[110:111] op_sel_hi:[1,0]
	v_mul_f32_e32 v176, 0xbfb8aa3b, v175
	v_lshlrev_b32_e32 v184, 16, v123
	s_waitcnt vmcnt(7)
	v_pk_mul_f32 v[48:49], v[76:77], v[48:49]
	v_pk_mul_f32 v[50:51], v[78:79], v[50:51]
	s_waitcnt vmcnt(3)
; DI unsigned pk_bf16(float lo, float hi) { f32x2 v = {lo, hi}; bf2_t b = __builtin_convertvector(v, bf2_t); return __builtin_bit_cast(unsigned, b); }
; DI float bf_lo(unsigned u) { return __uint_as_float(u << 16); }
; DI float bf_hi(unsigned u) { return __uint_as_float(u & 0xffff0000u); }
; DI float silu(float x) { return x * __builtin_amdgcn_rcpf(1.0f + __builtin_amdgcn_exp2f(-1.4426950408889634f * x)); }
; DI void store_head(const f32x16& o0, const f32x16& o1, float rs, const unsigned char* gl, int tr, int ch0, const float* gs, bf16_t* yp) {
;     u32x2 gt[8]; f32x4 gv[8];
; #pragma unroll
;     for (int q = 0; q < 8; ++q) { const int d = 32 * (q >> 2) + 8 * (q & 3); gt[q] = *(const u32x2*)(gl + gate_off(tr, ch0 + d)); gv[q] = *(const f32x4*)(gs + d); }
; #pragma unroll
;     for (int q = 0; q < 8; ++q) { const int d = 32 * (q >> 2) + 8 * (q & 3), g = q & 3;
;         const f32x16& o = (q >> 2) ? o1 : o0;
;         u32x2 w; w.x = pk_bf16(o[4 * g + 0] * rs * gv[q][0] * silu(bf_lo(gt[q].x)), o[4 * g + 1] * rs * gv[q][1] * silu(bf_hi(gt[q].x)));
;         w.y = pk_bf16(o[4 * g + 2] * rs * gv[q][2] * silu(bf_lo(gt[q].y)), o[4 * g + 3] * rs * gv[q][3] * silu(bf_hi(gt[q].y)));
;         *(u32x2*)(yp + d) = w; }
; DI void mixer_phase(const Params& p, unsigned char* ldsraw, int vid) {
;     ...
;             store_head(oA0, oA1, rsqrtf(totA * (1.0f / 512.0f) + EPS), gl, r, 64 * wid + 4 * hh, gs, Y + (size_t)tqA * 1024 + 64 * wid + 4 * hh);
;             store_head(oB0, oB1, rsqrtf(totB * (1.0f / 512.0f) + EPS), gl, r + 32, 64 * wid + 4 * hh, gs, Y + (size_t)tqB * 1024 + 64 * wid + 4 * hh);
	v_pk_mul_f32 v[32:33], v[32:33], v[84:85]
	v_pk_mul_f32 v[34:35], v[34:35], v[86:87]
	v_add_f32_e32 v172, 1.0, v174
	v_lshlrev_b32_e32 v174, 16, v122
	v_exp_f32_e32 v176, v176
	v_and_b32_e32 v185, 0xffff0000, v123
	v_mul_f32_e32 v123, 0xbfb8aa3b, v184
	v_pk_mul_f32 v[48:49], v[48:49], v[118:119]
	v_pk_mul_f32 v[50:51], v[50:51], v[120:121]
	v_pk_mul_f32 v[32:33], v[32:33], v[166:167]
	v_pk_mul_f32 v[34:35], v[34:35], v[156:157]
	v_mul_f32_e32 v122, 0xbfb8aa3b, v174
	v_exp_f32_e32 v183, v123
	v_mul_f32_e32 v123, 0xbfb8aa3b, v185
	v_cvt_pk_bf16_f32 v236, v48, v49
	v_cvt_pk_bf16_f32 v237, v50, v51
	v_cvt_pk_bf16_f32 v244, v32, v33
	v_cvt_pk_bf16_f32 v245, v34, v35
	v_exp_f32_e32 v122, v122
	v_exp_f32_e32 v187, v123
	v_and_b32_e32 v252, 32, v205
	v_lshrrev_b32_e32 v252, 2, v252
	v_mov_b32_e32 v253, 0
	v_lshl_add_u64 v[254:255], v[140:141], 0, v[252:253]
	v_pk_mul_f32 v[48:49], v[52:53], v[110:111] op_sel_hi:[1,0]
	v_pk_mul_f32 v[50:51], v[54:55], v[110:111] op_sel_hi:[1,0]
	v_pk_mul_f32 v[32:33], v[36:37], v[110:111] op_sel_hi:[1,0]
	v_pk_mul_f32 v[34:35], v[38:39], v[110:111] op_sel_hi:[1,0]
	v_rcp_f32_e32 v172, v172
	v_rcp_f32_e32 v173, v173
	v_pk_mul_f32 v[48:49], v[64:65], v[48:49]
	v_pk_mul_f32 v[50:51], v[66:67], v[50:51]
	s_waitcnt vmcnt(2)
	v_pk_mul_f32 v[32:33], v[32:33], v[72:73]
	v_pk_mul_f32 v[34:35], v[34:35], v[74:75]
	v_add_f32_e32 v176, 1.0, v176
	v_pk_mul_f32 v[48:49], v[48:49], v[124:125]
	v_pk_mul_f32 v[50:51], v[50:51], v[126:127]
	v_pk_mul_f32 v[32:33], v[32:33], v[168:169]
	v_pk_mul_f32 v[34:35], v[34:35], v[162:163]
	v_rcp_f32_e32 v123, v176
	v_add_f32_e32 v176, 1.0, v183
	v_cvt_pk_bf16_f32 v238, v48, v49
	v_cvt_pk_bf16_f32 v239, v50, v51
	v_cvt_pk_bf16_f32 v246, v32, v33
	v_cvt_pk_bf16_f32 v247, v34, v35
	v_add_f32_e32 v122, 1.0, v122
	v_rcp_f32_e32 v186, v176
	v_add_f32_e32 v176, 1.0, v187
	s_nop 1
	v_permlane32_swap_b32_e32 v236, v238
	v_permlane32_swap_b32_e32 v237, v239
	global_store_dwordx4 v[254:255], v[236:239], off
	v_pk_mul_f32 v[48:49], v[56:57], v[110:111] op_sel_hi:[1,0]
	v_pk_mul_f32 v[50:51], v[58:59], v[110:111] op_sel_hi:[1,0]
	s_nop 1
	v_permlane32_swap_b32_e32 v244, v246
	v_permlane32_swap_b32_e32 v245, v247
	global_store_dwordx4 v[254:255], v[244:247], off offset:64
	v_pk_mul_f32 v[32:33], v[40:41], v[110:111] op_sel_hi:[1,0]
	v_pk_mul_f32 v[34:35], v[42:43], v[110:111] op_sel_hi:[1,0]
	v_rcp_f32_e32 v122, v122
	v_rcp_f32_e32 v187, v176
	v_pk_mul_f32 v[104:105], v[172:173], v[130:131]
	v_pk_mul_f32 v[48:49], v[80:81], v[48:49]
	v_pk_mul_f32 v[50:51], v[82:83], v[50:51]
	s_waitcnt vmcnt(3)
	v_pk_mul_f32 v[32:33], v[32:33], v[92:93]
	v_pk_mul_f32 v[34:35], v[34:35], v[94:95]
	v_pk_mul_f32 v[48:49], v[48:49], v[128:129]
	v_pk_mul_f32 v[50:51], v[50:51], v[132:133]
	v_pk_mul_f32 v[32:33], v[32:33], v[170:171]
	v_pk_mul_f32 v[34:35], v[34:35], v[104:105]
	v_cvt_pk_bf16_f32 v240, v48, v49
	v_cvt_pk_bf16_f32 v241, v50, v51
	v_cvt_pk_bf16_f32 v248, v32, v33
	v_cvt_pk_bf16_f32 v249, v34, v35
	v_pk_mul_f32 v[48:49], v[60:61], v[110:111] op_sel_hi:[1,0]
	v_pk_mul_f32 v[50:51], v[62:63], v[110:111] op_sel_hi:[1,0]
	v_pk_mul_f32 v[32:33], v[44:45], v[110:111] op_sel_hi:[1,0]
	v_pk_mul_f32 v[34:35], v[46:47], v[110:111] op_sel_hi:[1,0]
	v_pk_mul_f32 v[106:107], v[122:123], v[174:175]
	v_pk_mul_f32 v[108:109], v[186:187], v[184:185]
	v_pk_mul_f32 v[48:49], v[48:49], v[68:69]
	v_pk_mul_f32 v[50:51], v[50:51], v[70:71]
	s_waitcnt vmcnt(2)
	v_pk_mul_f32 v[32:33], v[32:33], v[88:89]
	v_pk_mul_f32 v[34:35], v[34:35], v[90:91]
	v_pk_mul_f32 v[48:49], v[48:49], v[164:165]
	v_pk_mul_f32 v[50:51], v[50:51], v[142:143]
	v_pk_mul_f32 v[32:33], v[32:33], v[106:107]
	v_pk_mul_f32 v[34:35], v[34:35], v[108:109]
	v_cvt_pk_bf16_f32 v242, v48, v49
	v_cvt_pk_bf16_f32 v243, v50, v51
	v_cvt_pk_bf16_f32 v250, v32, v33
	v_cvt_pk_bf16_f32 v251, v34, v35
	s_nop 1
	v_permlane32_swap_b32_e32 v240, v242
	v_permlane32_swap_b32_e32 v241, v243
	global_store_dwordx4 v[254:255], v[240:243], off offset:32
	s_nop 1
	v_permlane32_swap_b32_e32 v248, v250
	v_permlane32_swap_b32_e32 v249, v251
	global_store_dwordx4 v[254:255], v[248:251], off offset:96
	global_load_dwordx4 v[56:59], v[98:99], off
	global_load_dwordx4 v[60:63], v[98:99], off offset:32
	v_mul_f32_e32 v32, 0x4b800000, v102
	v_cmp_gt_f32_e32 vcc, s98, v102
	v_or_b32_e32 v162, 0x10000, v159
	v_add3_u32 v35, v147, v162, v146
	v_cndmask_b32_e32 v32, v102, v32, vcc
	v_rsq_f32_e32 v33, v32
	v_or_b32_e32 v32, 32, v96
	v_ashrrev_i32_e32 v163, 3, v205
	s_mov_b64 s[0:1], -1
	v_mul_f32_e32 v34, 0x45800000, v33
	v_cndmask_b32_e32 v48, v33, v34, vcc
	v_ashrrev_i32_e32 v33, 31, v32
	v_lshlrev_b64 v[32:33], 11, v[32:33]
	v_lshl_add_u64 v[32:33], s[80:81], 0, v[32:33]
	v_lshl_add_u64 v[142:143], v[32:33], 0, v[100:101]
	v_add3_u32 v32, v135, v162, v134
	v_add3_u32 v33, v137, v162, v136
	v_add3_u32 v34, v139, v162, v138
	ds_read_b64 v[72:73], v32 offset:4096
	ds_read_b64 v[74:75], v33 offset:4096
	ds_read_b64 v[76:77], v34 offset:4096
	ds_read_b64 v[78:79], v35 offset:4096
	global_load_dwordx4 v[64:67], v[98:99], off offset:64
	global_load_dwordx4 v[68:71], v[98:99], off offset:96
	s_waitcnt lgkmcnt(3)
; DI unsigned pk_bf16(float lo, float hi) { f32x2 v = {lo, hi}; bf2_t b = __builtin_convertvector(v, bf2_t); return __builtin_bit_cast(unsigned, b); }
; DI float bf_lo(unsigned u) { return __uint_as_float(u << 16); }
; DI float bf_hi(unsigned u) { return __uint_as_float(u & 0xffff0000u); }
; DI float silu(float x) { return x * __builtin_amdgcn_rcpf(1.0f + __builtin_amdgcn_exp2f(-1.4426950408889634f * x)); }
; DI void store_head(const f32x16& o0, const f32x16& o1, float rs, const unsigned char* gl, int tr, int ch0, const float* gs, bf16_t* yp) {
;     u32x2 gt[8]; f32x4 gv[8];
; #pragma unroll
;     for (int q = 0; q < 8; ++q) { const int d = 32 * (q >> 2) + 8 * (q & 3); gt[q] = *(const u32x2*)(gl + gate_off(tr, ch0 + d)); gv[q] = *(const f32x4*)(gs + d); }
; #pragma unroll
;     for (int q = 0; q < 8; ++q) { const int d = 32 * (q >> 2) + 8 * (q & 3), g = q & 3;
;         const f32x16& o = (q >> 2) ? o1 : o0;
;         u32x2 w; w.x = pk_bf16(o[4 * g + 0] * rs * gv[q][0] * silu(bf_lo(gt[q].x)), o[4 * g + 1] * rs * gv[q][1] * silu(bf_hi(gt[q].x)));
;         w.y = pk_bf16(o[4 * g + 2] * rs * gv[q][2] * silu(bf_lo(gt[q].y)), o[4 * g + 3] * rs * gv[q][3] * silu(bf_hi(gt[q].y)));
;         *(u32x2*)(yp + d) = w; }
; }
	v_lshlrev_b32_e32 v80, 16, v72
	v_and_b32_e32 v81, 0xffff0000, v72
	v_mul_f32_e32 v36, 0xbfb8aa3b, v80
	v_exp_f32_e32 v36, v36
	v_mul_f32_e32 v37, 0xbfb8aa3b, v81
	v_exp_f32_e32 v37, v37
	v_add3_u32 v32, v149, v162, v148
	v_add3_u32 v33, v151, v162, v150
	global_load_dwordx4 v[44:47], v[98:99], off offset:128
	global_load_dwordx4 v[40:43], v[98:99], off offset:160
	v_add3_u32 v34, v153, v162, v152
	v_add3_u32 v35, v155, v162, v154
	ds_read_b64 v[82:83], v32 offset:4096
	ds_read_b64 v[54:55], v33 offset:4096
	ds_read_b64 v[52:53], v34 offset:4096
	ds_read_b64 v[50:51], v35 offset:4096
	v_add_f32_e32 v32, 1.0, v36
	v_rcp_f32_e32 v84, v32
	v_add_f32_e32 v32, 1.0, v37
	v_rcp_f32_e32 v85, v32
	v_lshlrev_b32_e32 v72, 16, v73
	v_pk_mul_f32 v[16:17], v[16:17], v[48:49] op_sel_hi:[1,0]
	v_and_b32_e32 v73, 0xffff0000, v73
	v_mul_f32_e32 v49, 0xbfb8aa3b, v72
	v_exp_f32_e32 v49, v49
	global_load_dwordx4 v[36:39], v[98:99], off offset:192
	global_load_dwordx4 v[32:35], v[98:99], off offset:224
	s_and_b64 vcc, exec, s[76:77]
	v_add_u32_e32 v146, s38, v163
	v_add_f32_e32 v49, 1.0, v49
	v_lshlrev_b32_e32 v164, 4, v163
	s_waitcnt vmcnt(7)
	v_pk_mul_f32 v[16:17], v[16:17], v[56:57]
	v_pk_mul_f32 v[56:57], v[84:85], v[80:81]
	v_mul_f32_e32 v80, 0xbfb8aa3b, v73
	v_exp_f32_e32 v80, v80
	v_pk_mul_f32 v[16:17], v[16:17], v[56:57]
	v_rcp_f32_e32 v56, v49
	v_cvt_pk_bf16_f32 v236, v16, v17
	v_add_f32_e32 v49, 1.0, v80
	v_rcp_f32_e32 v57, v49
	v_pk_mul_f32 v[18:19], v[18:19], v[48:49] op_sel_hi:[1,0]
	v_pk_mul_f32 v[56:57], v[56:57], v[72:73]
	v_pk_mul_f32 v[18:19], v[18:19], v[58:59]
	s_nop 0
	v_pk_mul_f32 v[18:19], v[18:19], v[56:57]
	s_waitcnt lgkmcnt(6)
	v_lshlrev_b32_e32 v56, 16, v74
	v_and_b32_e32 v57, 0xffff0000, v74
	v_mul_f32_e32 v17, 0xbfb8aa3b, v56
	v_exp_f32_e32 v49, v17
	v_mul_f32_e32 v17, 0xbfb8aa3b, v57
	v_exp_f32_e32 v58, v17
	v_cvt_pk_bf16_f32 v237, v18, v19
	v_add_f32_e32 v18, 1.0, v49
	v_rcp_f32_e32 v18, v18
	v_add_f32_e32 v19, 1.0, v58
	v_rcp_f32_e32 v19, v19
	v_and_b32_e32 v252, 32, v205
	v_lshrrev_b32_e32 v252, 2, v252
	v_mov_b32_e32 v253, 0
	v_lshl_add_u64 v[254:255], v[142:143], 0, v[252:253]
	v_pk_mul_f32 v[16:17], v[20:21], v[48:49] op_sel_hi:[1,0]
	v_lshlrev_b32_e32 v20, 16, v75
	v_and_b32_e32 v21, 0xffff0000, v75
	v_pk_mul_f32 v[18:19], v[18:19], v[56:57]
	v_mul_f32_e32 v49, 0xbfb8aa3b, v20
	v_mul_f32_e32 v56, 0xbfb8aa3b, v21
	v_exp_f32_e32 v49, v49
	v_exp_f32_e32 v56, v56
	s_waitcnt vmcnt(6)
	v_pk_mul_f32 v[16:17], v[16:17], v[60:61]
	v_pk_mul_f32 v[22:23], v[22:23], v[48:49] op_sel_hi:[1,0]
	v_pk_mul_f32 v[16:17], v[16:17], v[18:19]
	v_add_f32_e32 v18, 1.0, v49
	v_add_f32_e32 v19, 1.0, v56
	v_rcp_f32_e32 v18, v18
	v_rcp_f32_e32 v19, v19
	v_cvt_pk_bf16_f32 v238, v16, v17
	v_pk_mul_f32 v[22:23], v[22:23], v[62:63]
	v_pk_mul_f32 v[0:1], v[0:1], v[48:49] op_sel_hi:[1,0]
	v_pk_mul_f32 v[18:19], v[18:19], v[20:21]
	s_waitcnt lgkmcnt(5)
	v_lshlrev_b32_e32 v20, 16, v76
	v_and_b32_e32 v21, 0xffff0000, v76
	v_mul_f32_e32 v17, 0xbfb8aa3b, v20
	v_pk_mul_f32 v[18:19], v[22:23], v[18:19]
	v_exp_f32_e32 v22, v17
	v_mul_f32_e32 v17, 0xbfb8aa3b, v21
	v_exp_f32_e32 v23, v17
	v_cvt_pk_bf16_f32 v239, v18, v19
	v_add_f32_e32 v18, 1.0, v22
	v_rcp_f32_e32 v18, v18
	v_add_f32_e32 v19, 1.0, v23
	v_rcp_f32_e32 v19, v19
	s_nop 1
	v_permlane32_swap_b32_e32 v236, v238
	v_permlane32_swap_b32_e32 v237, v239
	global_store_dwordx4 v[254:255], v[236:239], off
	v_pk_mul_f32 v[16:17], v[24:25], v[48:49] op_sel_hi:[1,0]
	s_waitcnt vmcnt(4)
	v_pk_mul_f32 v[0:1], v[0:1], v[44:45]
	v_pk_mul_f32 v[18:19], v[18:19], v[20:21]
	v_lshlrev_b32_e32 v20, 16, v77
	v_and_b32_e32 v21, 0xffff0000, v77
	v_mul_f32_e32 v22, 0xbfb8aa3b, v20
	v_mul_f32_e32 v23, 0xbfb8aa3b, v21
	v_exp_f32_e32 v22, v22
	v_exp_f32_e32 v23, v23
	v_pk_mul_f32 v[16:17], v[16:17], v[64:65]
	v_pk_mul_f32 v[2:3], v[2:3], v[48:49] op_sel_hi:[1,0]
	v_pk_mul_f32 v[16:17], v[16:17], v[18:19]
	v_add_f32_e32 v18, 1.0, v22
	v_add_f32_e32 v19, 1.0, v23
	v_rcp_f32_e32 v18, v18
	v_rcp_f32_e32 v19, v19
	v_pk_mul_f32 v[22:23], v[26:27], v[48:49] op_sel_hi:[1,0]
	v_cvt_pk_bf16_f32 v240, v16, v17
	v_pk_mul_f32 v[22:23], v[22:23], v[66:67]
	v_pk_mul_f32 v[18:19], v[18:19], v[20:21]
	s_waitcnt lgkmcnt(4)
	v_lshlrev_b32_e32 v20, 16, v78
	v_and_b32_e32 v21, 0xffff0000, v78
	v_mul_f32_e32 v17, 0xbfb8aa3b, v20
	v_pk_mul_f32 v[18:19], v[22:23], v[18:19]
	v_exp_f32_e32 v22, v17
	v_mul_f32_e32 v17, 0xbfb8aa3b, v21
	v_exp_f32_e32 v23, v17
	v_cvt_pk_bf16_f32 v241, v18, v19
	v_add_f32_e32 v18, 1.0, v22
	v_rcp_f32_e32 v18, v18
	v_add_f32_e32 v19, 1.0, v23
	v_rcp_f32_e32 v19, v19
	v_pk_mul_f32 v[16:17], v[28:29], v[48:49] op_sel_hi:[1,0]
	v_pk_mul_f32 v[2:3], v[2:3], v[46:47]
	v_pk_mul_f32 v[18:19], v[18:19], v[20:21]
	v_lshlrev_b32_e32 v20, 16, v79
	v_and_b32_e32 v21, 0xffff0000, v79
	v_mul_f32_e32 v22, 0xbfb8aa3b, v20
	v_mul_f32_e32 v23, 0xbfb8aa3b, v21
	v_exp_f32_e32 v22, v22
	v_exp_f32_e32 v23, v23
	v_pk_mul_f32 v[16:17], v[16:17], v[68:69]
	v_pk_mul_f32 v[6:7], v[6:7], v[48:49] op_sel_hi:[1,0]
	v_pk_mul_f32 v[16:17], v[16:17], v[18:19]
	v_add_f32_e32 v18, 1.0, v22
	v_add_f32_e32 v19, 1.0, v23
	v_rcp_f32_e32 v18, v18
	v_rcp_f32_e32 v19, v19
	v_pk_mul_f32 v[22:23], v[30:31], v[48:49] op_sel_hi:[1,0]
	v_cvt_pk_bf16_f32 v242, v16, v17
	v_pk_mul_f32 v[22:23], v[22:23], v[70:71]
	v_pk_mul_f32 v[18:19], v[18:19], v[20:21]
	s_waitcnt lgkmcnt(3)
	v_lshlrev_b32_e32 v20, 16, v82
	v_and_b32_e32 v21, 0xffff0000, v82
	v_mul_f32_e32 v17, 0xbfb8aa3b, v20
	v_pk_mul_f32 v[18:19], v[22:23], v[18:19]
	v_exp_f32_e32 v22, v17
	v_mul_f32_e32 v17, 0xbfb8aa3b, v21
	v_exp_f32_e32 v23, v17
	v_cvt_pk_bf16_f32 v243, v18, v19
	v_add_f32_e32 v18, 1.0, v22
	v_rcp_f32_e32 v18, v18
	v_add_f32_e32 v19, 1.0, v23
	v_rcp_f32_e32 v19, v19
	s_nop 1
	v_permlane32_swap_b32_e32 v240, v242
	v_permlane32_swap_b32_e32 v241, v243
	global_store_dwordx4 v[254:255], v[240:243], off offset:32
	s_waitcnt vmcnt(4)
; DI unsigned pk_bf16(float lo, float hi) { f32x2 v = {lo, hi}; bf2_t b = __builtin_convertvector(v, bf2_t); return __builtin_bit_cast(unsigned, b); }
; DI float bf_lo(unsigned u) { return __uint_as_float(u << 16); }
; DI float bf_hi(unsigned u) { return __uint_as_float(u & 0xffff0000u); }
; DI float silu(float x) { return x * __builtin_amdgcn_rcpf(1.0f + __builtin_amdgcn_exp2f(-1.4426950408889634f * x)); }
; DI void store_head(const f32x16& o0, const f32x16& o1, float rs, const unsigned char* gl, int tr, int ch0, const float* gs, bf16_t* yp) {
;     u32x2 gt[8]; f32x4 gv[8];
; #pragma unroll
;     for (int q = 0; q < 8; ++q) { const int d = 32 * (q >> 2) + 8 * (q & 3); gt[q] = *(const u32x2*)(gl + gate_off(tr, ch0 + d)); gv[q] = *(const f32x4*)(gs + d); }
; #pragma unroll
;     for (int q = 0; q < 8; ++q) { const int d = 32 * (q >> 2) + 8 * (q & 3), g = q & 3;
;         const f32x16& o = (q >> 2) ? o1 : o0;
;         u32x2 w; w.x = pk_bf16(o[4 * g + 0] * rs * gv[q][0] * silu(bf_lo(gt[q].x)), o[4 * g + 1] * rs * gv[q][1] * silu(bf_hi(gt[q].x)));
;         w.y = pk_bf16(o[4 * g + 2] * rs * gv[q][2] * silu(bf_lo(gt[q].y)), o[4 * g + 3] * rs * gv[q][3] * silu(bf_hi(gt[q].y)));
;         *(u32x2*)(yp + d) = w; }
; }
	v_pk_mul_f32 v[6:7], v[6:7], v[42:43]
	v_pk_mul_f32 v[16:17], v[18:19], v[20:21]
	v_lshlrev_b32_e32 v18, 16, v83
	v_and_b32_e32 v19, 0xffff0000, v83
	v_mul_f32_e32 v20, 0xbfb8aa3b, v18
	v_mul_f32_e32 v21, 0xbfb8aa3b, v19
	v_exp_f32_e32 v20, v20
	v_exp_f32_e32 v21, v21
	v_pk_mul_f32 v[0:1], v[0:1], v[16:17]
	v_add_f32_e32 v16, 1.0, v20
	v_add_f32_e32 v17, 1.0, v21
	v_rcp_f32_e32 v16, v16
	v_rcp_f32_e32 v17, v17
	v_cvt_pk_bf16_f32 v244, v0, v1
	v_pk_mul_f32 v[16:17], v[16:17], v[18:19]
	s_nop 0
	v_pk_mul_f32 v[2:3], v[2:3], v[16:17]
	s_waitcnt lgkmcnt(2)
	v_lshlrev_b32_e32 v16, 16, v54
	v_and_b32_e32 v17, 0xffff0000, v54
	v_mul_f32_e32 v1, 0xbfb8aa3b, v16
	v_exp_f32_e32 v18, v1
	v_mul_f32_e32 v1, 0xbfb8aa3b, v17
	v_exp_f32_e32 v19, v1
	v_cvt_pk_bf16_f32 v245, v2, v3
	v_add_f32_e32 v2, 1.0, v18
	v_rcp_f32_e32 v2, v2
	v_add_f32_e32 v3, 1.0, v19
	v_rcp_f32_e32 v3, v3
	v_pk_mul_f32 v[0:1], v[4:5], v[48:49] op_sel_hi:[1,0]
	v_lshlrev_b32_e32 v4, 16, v55
	v_and_b32_e32 v5, 0xffff0000, v55
	v_pk_mul_f32 v[2:3], v[2:3], v[16:17]
	v_mul_f32_e32 v16, 0xbfb8aa3b, v4
	v_mul_f32_e32 v17, 0xbfb8aa3b, v5
	v_exp_f32_e32 v16, v16
	v_exp_f32_e32 v17, v17
	v_pk_mul_f32 v[0:1], v[0:1], v[40:41]
	s_nop 0
	v_pk_mul_f32 v[0:1], v[0:1], v[2:3]
	v_add_f32_e32 v2, 1.0, v16
	v_add_f32_e32 v3, 1.0, v17
	v_rcp_f32_e32 v2, v2
	v_rcp_f32_e32 v3, v3
	v_cvt_pk_bf16_f32 v246, v0, v1
	v_pk_mul_f32 v[2:3], v[2:3], v[4:5]
	s_waitcnt lgkmcnt(1)
	v_lshlrev_b32_e32 v4, 16, v52
	v_and_b32_e32 v5, 0xffff0000, v52
	v_mul_f32_e32 v1, 0xbfb8aa3b, v4
	v_pk_mul_f32 v[2:3], v[6:7], v[2:3]
	v_exp_f32_e32 v6, v1
	v_mul_f32_e32 v1, 0xbfb8aa3b, v5
	v_exp_f32_e32 v7, v1
	v_cvt_pk_bf16_f32 v247, v2, v3
	v_add_f32_e32 v2, 1.0, v6
	v_rcp_f32_e32 v2, v2
	v_add_f32_e32 v3, 1.0, v7
	v_rcp_f32_e32 v3, v3
	s_nop 1
	v_permlane32_swap_b32_e32 v244, v246
	v_permlane32_swap_b32_e32 v245, v247
	global_store_dwordx4 v[254:255], v[244:247], off offset:64
	v_pk_mul_f32 v[0:1], v[8:9], v[48:49] op_sel_hi:[1,0]
	v_pk_mul_f32 v[2:3], v[2:3], v[4:5]
	v_lshlrev_b32_e32 v4, 16, v53
	v_and_b32_e32 v5, 0xffff0000, v53
	v_mul_f32_e32 v6, 0xbfb8aa3b, v4
	v_mul_f32_e32 v7, 0xbfb8aa3b, v5
	v_exp_f32_e32 v6, v6
	v_exp_f32_e32 v7, v7
	s_waitcnt vmcnt(4)
	v_pk_mul_f32 v[0:1], v[0:1], v[36:37]
	s_nop 0
	v_pk_mul_f32 v[0:1], v[0:1], v[2:3]
	v_add_f32_e32 v2, 1.0, v6
	v_add_f32_e32 v3, 1.0, v7
	v_rcp_f32_e32 v2, v2
	v_rcp_f32_e32 v3, v3
	v_pk_mul_f32 v[6:7], v[10:11], v[48:49] op_sel_hi:[1,0]
	v_cvt_pk_bf16_f32 v248, v0, v1
	v_pk_mul_f32 v[6:7], v[6:7], v[38:39]
	v_pk_mul_f32 v[2:3], v[2:3], v[4:5]
	s_waitcnt lgkmcnt(0)
	v_lshlrev_b32_e32 v4, 16, v50
	v_and_b32_e32 v5, 0xffff0000, v50
	v_mul_f32_e32 v1, 0xbfb8aa3b, v4
	v_pk_mul_f32 v[2:3], v[6:7], v[2:3]
	v_exp_f32_e32 v6, v1
	v_mul_f32_e32 v1, 0xbfb8aa3b, v5
	v_exp_f32_e32 v7, v1
	v_cvt_pk_bf16_f32 v249, v2, v3
	v_add_f32_e32 v2, 1.0, v6
	v_rcp_f32_e32 v2, v2
	v_add_f32_e32 v3, 1.0, v7
	v_rcp_f32_e32 v3, v3
	v_pk_mul_f32 v[0:1], v[12:13], v[48:49] op_sel_hi:[1,0]
	v_pk_mul_f32 v[2:3], v[2:3], v[4:5]
	v_lshlrev_b32_e32 v4, 16, v51
	v_and_b32_e32 v5, 0xffff0000, v51
	v_mul_f32_e32 v6, 0xbfb8aa3b, v4
	v_mul_f32_e32 v7, 0xbfb8aa3b, v5
	v_exp_f32_e32 v6, v6
	v_exp_f32_e32 v7, v7
	s_waitcnt vmcnt(3)
	v_pk_mul_f32 v[0:1], v[0:1], v[32:33]
	s_nop 0
	v_pk_mul_f32 v[0:1], v[0:1], v[2:3]
	v_add_f32_e32 v2, 1.0, v6
	v_add_f32_e32 v3, 1.0, v7
	v_rcp_f32_e32 v2, v2
	v_rcp_f32_e32 v3, v3
	v_pk_mul_f32 v[6:7], v[14:15], v[48:49] op_sel_hi:[1,0]
	v_cvt_pk_bf16_f32 v250, v0, v1
	v_pk_mul_f32 v[6:7], v[6:7], v[34:35]
	v_pk_mul_f32 v[2:3], v[2:3], v[4:5]
	s_nop 0
	v_pk_mul_f32 v[2:3], v[6:7], v[2:3]
	s_nop 0
	v_cvt_pk_bf16_f32 v251, v2, v3
	s_nop 1
	v_permlane32_swap_b32_e32 v248, v250
	v_permlane32_swap_b32_e32 v249, v251
	global_store_dwordx4 v[254:255], v[248:251], off offset:96
	s_cbranch_vccz .LBB0_432
; DI void conv_tok(const ConvW& cw, const bf16_t* RR, int t, int ch, float (&y)[8]) {
;     const int t1 = t >= 1 ? t - 1 : 0, t2 = t >= 2 ? t - 2 : 0;
;     const float k1 = t >= 1 ? 1.f : 0.f, k2 = t >= 2 ? 1.f : 0.f;
;     const bf16_t* rp0 = RR + (size_t)t * 2048 + ch; const bf16_t* rp1 = RR + (size_t)t1 * 2048 + ch; const bf16_t* rp2 = RR + (size_t)t2 * 2048 + ch;
;     const u32x4 u0 = *(const u32x4*)rp0, b0 = *(const u32x4*)(rp0 + 256), c0 = *(const u32x4*)(rp0 + 512);
;     const u32x4 u1 = *(const u32x4*)rp1, c1 = *(const u32x4*)(rp1 + 512), u2 = *(const u32x4*)rp2, c2 = *(const u32x4*)(rp2 + 512);
; #pragma unroll
;     for (int e2 = 0; e2 < 4; ++e2) {
;         const int j = (2 * e2) & 3;
;         const f32x4& w0 = e2 < 2 ? cw.w0a : cw.w0b; const f32x4& w1 = e2 < 2 ? cw.w1a : cw.w1b; const f32x4& w2 = e2 < 2 ? cw.w2a : cw.w2b; const f32x4& bb = e2 < 2 ? cw.ba : cw.bb;
; DI void mixer_phase(const Params& p, unsigned char* ldsraw, int vid) {
;     ...
;                 const int cgp = wid - 4, chunk = ln & 7, trow = ln >> 3, ch = 64 * cgp + 8 * chunk;
;                 ConvW cw; { const float* wp = p.conv_w + ch; const float* bp = p.conv_b + ch;
;                     cw.w0a = *(const f32x4*)wp; cw.w0b = *(const f32x4*)(wp + 4); cw.w1a = *(const f32x4*)(wp + 256); cw.w1b = *(const f32x4*)(wp + 260);
;                     cw.w2a = *(const f32x4*)(wp + 512); cw.w2b = *(const f32x4*)(wp + 516); cw.ba = *(const f32x4*)bp; cw.bb = *(const f32x4*)(bp + 4); }
; #pragma unroll
;                 for (int j = 0; j < 8; ++j) {
;                     float y[8]; conv_tok(cw, RR, t0 + trow + 8 * j, ch, y);
;                     float ss = 0.f;
; #pragma unroll
;                     for (int e = 0; e < 8; ++e) ss += y[e] * y[e];
;                     ss += __shfl_xor(ss, 1); ss += __shfl_xor(ss, 2); ss += __shfl_xor(ss, 4);
;                     const int tk = trow + 8 * j;
;                     if (chunk == 0) lf[768 + 128 * (tk >> 5) + cgp * 32 + (tk & 31)] = ss;
;                     f32x16& dst = (j < 2) ? a0 : (j < 4) ? a1 : (j < 6) ? b0 : b1;
; #pragma unroll
;                     for (int e = 0; e < 8; ++e) dst[(j & 1) * 8 + e] = y[e];
;                     if ((j & 3) == 3) __builtin_amdgcn_sched_barrier(0);
;                 }
	v_and_b32_e32 v69, 7, v205
	v_max_i32_e32 v0, 2, v146
	v_lshl_or_b32 v176, v69, 3, s93
	v_add_u32_e32 v0, -2, v0
	v_ashrrev_i32_e32 v147, 31, v146
	v_mov_b32_e32 v1, v177
	v_lshl_add_u64 v[32:33], v[176:177], 1, s[44:45]
	v_lshlrev_b64 v[2:3], 12, v[146:147]
	v_lshlrev_b64 v[0:1], 12, v[0:1]
	v_lshl_add_u64 v[2:3], v[32:33], 0, v[2:3]
	v_lshl_add_u64 v[0:1], v[32:33], 0, v[0:1]
	global_load_dwordx4 v[36:39], v[2:3], off offset:512
	global_load_dwordx4 v[40:43], v[0:1], off offset:1024
	global_load_dwordx4 v[44:47], v[2:3], off
	global_load_dwordx4 v[52:55], v[2:3], off offset:1024
	global_load_dwordx4 v[56:59], v[0:1], off
	v_max_i32_e32 v2, 1, v146
	v_lshlrev_b64 v[0:1], 2, v[176:177]
	v_add_u32_e32 v176, -1, v2
	v_lshlrev_b64 v[2:3], 12, v[176:177]
	v_lshl_add_u64 v[2:3], v[32:33], 0, v[2:3]
	global_load_dwordx4 v[60:63], v[2:3], off
	global_load_dwordx4 v[64:67], v[2:3], off offset:1024
	v_lshl_add_u64 v[2:3], s[48:49], 0, v[0:1]
	global_load_dwordx4 v[28:31], v[2:3], off
	global_load_dwordx4 v[24:27], v[2:3], off offset:1024
	global_load_dwordx4 v[16:19], v[2:3], off offset:2048
	v_lshl_add_u64 v[4:5], s[50:51], 0, v[0:1]
	global_load_dwordx4 v[20:23], v[4:5], off
	global_load_dwordx4 v[12:15], v[2:3], off offset:16
	global_load_dwordx4 v[8:11], v[2:3], off offset:1040
	s_nop 0
	global_load_dwordx4 v[0:3], v[2:3], off offset:2064
	s_nop 0
	global_load_dwordx4 v[4:7], v[4:5], off offset:16
	v_cmp_lt_i32_e32 vcc, 0, v146
	v_xor_b32_e32 v34, 1, v202
	s_waitcnt vmcnt(13)
	v_lshlrev_b32_e32 v50, 16, v40
	v_cndmask_b32_e64 v68, 0, 1.0, vcc
	v_cmp_lt_i32_e32 vcc, 1, v146
	s_waitcnt vmcnt(10)
	v_lshlrev_b32_e32 v78, 16, v56
	v_and_b32_e32 v79, 0xffff0000, v56
	v_cndmask_b32_e64 v70, 0, 1.0, vcc
	v_lshlrev_b32_e32 v56, 16, v57
	v_and_b32_e32 v57, 0xffff0000, v57
	v_and_b32_e32 v51, 0xffff0000, v40
	v_lshlrev_b32_e32 v72, 16, v44
	v_and_b32_e32 v73, 0xffff0000, v44
	v_lshlrev_b32_e32 v74, 16, v52
	v_and_b32_e32 v75, 0xffff0000, v52
	v_lshlrev_b32_e32 v40, 16, v41
	v_and_b32_e32 v41, 0xffff0000, v41
	v_lshlrev_b32_e32 v44, 16, v45
	v_and_b32_e32 v45, 0xffff0000, v45
	v_lshlrev_b32_e32 v52, 16, v53
	v_and_b32_e32 v53, 0xffff0000, v53
	s_waitcnt vmcnt(9)
	v_lshlrev_b32_e32 v82, 16, v60
	v_and_b32_e32 v83, 0xffff0000, v60
	v_lshlrev_b32_e32 v60, 16, v61
	v_and_b32_e32 v61, 0xffff0000, v61
	v_pk_mul_f32 v[56:57], v[70:71], v[56:57] op_sel_hi:[0,1]
	s_waitcnt vmcnt(8)
	v_lshlrev_b32_e32 v84, 16, v64
	v_and_b32_e32 v85, 0xffff0000, v64
	v_lshlrev_b32_e32 v64, 16, v65
	v_and_b32_e32 v65, 0xffff0000, v65
	v_pk_mul_f32 v[44:45], v[44:45], v[52:53]
	v_pk_mul_f32 v[52:53], v[70:71], v[78:79] op_sel_hi:[0,1]
	v_pk_mul_f32 v[60:61], v[68:69], v[60:61] op_sel_hi:[0,1]
	v_pk_mul_f32 v[40:41], v[56:57], v[40:41]
	v_pk_mul_f32 v[72:73], v[72:73], v[74:75]
	v_pk_mul_f32 v[74:75], v[68:69], v[82:83] op_sel_hi:[0,1]
	v_pk_mul_f32 v[50:51], v[52:53], v[50:51]
	v_pk_mul_f32 v[56:57], v[60:61], v[64:65]
	s_waitcnt vmcnt(7)
	v_pk_mul_f32 v[40:41], v[30:31], v[40:41]
	v_pk_mul_f32 v[52:53], v[74:75], v[84:85]
	v_pk_mul_f32 v[50:51], v[28:29], v[50:51]
	s_waitcnt vmcnt(6)
	v_pk_fma_f32 v[40:41], v[26:27], v[56:57], v[40:41]
	v_pk_fma_f32 v[50:51], v[24:25], v[52:53], v[50:51]
	s_waitcnt vmcnt(5)
	v_pk_fma_f32 v[40:41], v[18:19], v[44:45], v[40:41]
	v_lshlrev_b32_e32 v48, 16, v36
	v_and_b32_e32 v49, 0xffff0000, v36
	v_lshlrev_b32_e32 v36, 16, v37
	v_and_b32_e32 v37, 0xffff0000, v37
	v_lshlrev_b32_e32 v80, 16, v58
	v_and_b32_e32 v81, 0xffff0000, v58
	v_pk_fma_f32 v[50:51], v[16:17], v[72:73], v[50:51]
	s_waitcnt vmcnt(4)
	v_pk_add_f32 v[40:41], v[22:23], v[40:41]
	v_pk_add_f32 v[44:45], v[20:21], v[50:51]
	v_pk_mul_f32 v[50:51], v[40:41], v[36:37]
	v_pk_mul_f32 v[36:37], v[70:71], v[80:81] op_sel_hi:[0,1]
	v_lshlrev_b32_e32 v40, 16, v42
	v_and_b32_e32 v41, 0xffff0000, v42
	v_pk_mul_f32 v[36:37], v[36:37], v[40:41]
	v_lshlrev_b32_e32 v40, 16, v62
	v_and_b32_e32 v41, 0xffff0000, v62
	v_pk_mul_f32 v[48:49], v[44:45], v[48:49]
	v_pk_mul_f32 v[40:41], v[68:69], v[40:41] op_sel_hi:[0,1]
	v_lshlrev_b32_e32 v44, 16, v66
	v_and_b32_e32 v45, 0xffff0000, v66
	s_waitcnt vmcnt(3)
	v_pk_mul_f32 v[36:37], v[12:13], v[36:37]
	v_pk_mul_f32 v[40:41], v[40:41], v[44:45]
	v_lshlrev_b32_e32 v44, 16, v54
	s_waitcnt vmcnt(2)
	v_pk_fma_f32 v[36:37], v[8:9], v[40:41], v[36:37]
	v_lshlrev_b32_e32 v40, 16, v46
	v_and_b32_e32 v41, 0xffff0000, v46
	v_and_b32_e32 v45, 0xffff0000, v54
	v_pk_mul_f32 v[40:41], v[40:41], v[44:45]
	v_lshlrev_b32_e32 v76, 16, v38
	s_waitcnt vmcnt(1)
	v_pk_fma_f32 v[36:37], v[0:1], v[40:41], v[36:37]
	v_and_b32_e32 v77, 0xffff0000, v38
	s_waitcnt vmcnt(0)
	v_pk_add_f32 v[36:37], v[4:5], v[36:37]
	v_lshlrev_b32_e32 v38, 16, v59
	v_pk_mul_f32 v[52:53], v[36:37], v[76:77]
	v_lshlrev_b32_e32 v36, 16, v39
	v_and_b32_e32 v37, 0xffff0000, v39
	v_and_b32_e32 v39, 0xffff0000, v59
	v_pk_mul_f32 v[38:39], v[70:71], v[38:39] op_sel_hi:[0,1]
	v_lshlrev_b32_e32 v40, 16, v43
	v_and_b32_e32 v41, 0xffff0000, v43
	v_pk_mul_f32 v[38:39], v[38:39], v[40:41]
	v_lshlrev_b32_e32 v40, 16, v63
	v_and_b32_e32 v41, 0xffff0000, v63
	v_pk_mul_f32 v[40:41], v[68:69], v[40:41] op_sel_hi:[0,1]
	v_lshlrev_b32_e32 v42, 16, v67
	v_and_b32_e32 v43, 0xffff0000, v67
	v_pk_mul_f32 v[38:39], v[14:15], v[38:39]
	v_pk_mul_f32 v[40:41], v[40:41], v[42:43]
	v_lshlrev_b32_e32 v42, 16, v55
	v_pk_fma_f32 v[38:39], v[10:11], v[40:41], v[38:39]
	v_lshlrev_b32_e32 v40, 16, v47
	v_and_b32_e32 v41, 0xffff0000, v47
	v_and_b32_e32 v43, 0xffff0000, v55
	v_pk_mul_f32 v[40:41], v[40:41], v[42:43]
	v_cmp_lt_i32_e32 vcc, v34, v204
	v_pk_fma_f32 v[38:39], v[2:3], v[40:41], v[38:39]
	v_pk_mul_f32 v[40:41], v[52:53], v[52:53]
	v_pk_add_f32 v[38:39], v[6:7], v[38:39]
	v_cndmask_b32_e32 v34, v202, v34, vcc
	v_pk_mul_f32 v[54:55], v[38:39], v[36:37]
	v_pk_mul_f32 v[36:37], v[48:49], v[48:49]
	v_pk_mul_f32 v[38:39], v[50:51], v[50:51]
	v_add_f32_e32 v35, v36, v37
	v_add_f32_e32 v35, v38, v35
	v_add_f32_e32 v35, v39, v35
	v_add_f32_e32 v35, v40, v35
	v_pk_mul_f32 v[42:43], v[54:55], v[54:55]
	v_add_f32_e32 v35, v41, v35
	v_add_f32_e32 v35, v42, v35
	v_lshlrev_b32_e32 v34, 2, v34
	v_add_f32_e32 v36, v43, v35
	ds_bpermute_b32 v37, v34, v36
	v_xor_b32_e32 v35, 2, v202
	v_cmp_lt_i32_e32 vcc, v35, v204
	s_waitcnt lgkmcnt(0)
	v_add_f32_e32 v37, v36, v37
	v_cndmask_b32_e32 v35, v202, v35, vcc
	v_lshlrev_b32_e32 v35, 2, v35
	ds_bpermute_b32 v38, v35, v37
	v_xor_b32_e32 v36, 4, v202
	v_cmp_lt_i32_e32 vcc, v36, v204
	s_waitcnt lgkmcnt(0)
	v_add_f32_e32 v38, v37, v38
	v_cndmask_b32_e32 v36, v202, v36, vcc
	v_lshlrev_b32_e32 v36, 2, v36
	ds_bpermute_b32 v39, v36, v38
	v_cmp_eq_u32_e32 vcc, 0, v69
	v_and_b32_e32 v37, 0xfffffe00, v164
	s_and_saveexec_b64 s[0:1], vcc
	s_cbranch_execz .LBB0_417
	v_lshrrev_b32_e32 v40, 1, v205
	v_and_b32_e32 v40, 0x7c, v40
	v_add3_u32 v40, s75, v37, v40
	s_waitcnt lgkmcnt(0)
	v_add_f32_e32 v38, v38, v39
	ds_write_b32 v40, v38 offset:3072

; DI unsigned pk_bf16(float lo, float hi) { f32x2 v = {lo, hi}; bf2_t b = __builtin_convertvector(v, bf2_t); return __builtin_bit_cast(unsigned, b); }
; DI float bf_lo(unsigned u) { return __uint_as_float(u << 16); }
; DI float bf_hi(unsigned u) { return __uint_as_float(u & 0xffff0000u); }
; DI float silu(float x) { return x * __builtin_amdgcn_rcpf(1.0f + __builtin_amdgcn_exp2f(-1.4426950408889634f * x)); }
; DI void store_head(const f32x16& o0, const f32x16& o1, float rs, const unsigned char* gl, int tr, int ch0, const float* gs, bf16_t* yp) {
;     u32x2 gt[8]; f32x4 gv[8];
; #pragma unroll
;     for (int q = 0; q < 8; ++q) { const int d = 32 * (q >> 2) + 8 * (q & 3); gt[q] = *(const u32x2*)(gl + gate_off(tr, ch0 + d)); gv[q] = *(const f32x4*)(gs + d); }
; #pragma unroll
;     for (int q = 0; q < 8; ++q) { const int d = 32 * (q >> 2) + 8 * (q & 3), g = q & 3;
;         const f32x16& o = (q >> 2) ? o1 : o0;
;         u32x2 w; w.x = pk_bf16(o[4 * g + 0] * rs * gv[q][0] * silu(bf_lo(gt[q].x)), o[4 * g + 1] * rs * gv[q][1] * silu(bf_hi(gt[q].x)));
;         w.y = pk_bf16(o[4 * g + 2] * rs * gv[q][2] * silu(bf_lo(gt[q].y)), o[4 * g + 3] * rs * gv[q][3] * silu(bf_hi(gt[q].y)));
; DI void mixer_phase(const Params& p, unsigned char* ldsraw, int vid) {
;     ...
;             __syncthreads();
;             if (wid < 4) {
;                 const float totA = (lf[512 + r] + lf[544 + r]) + (lf[576 + r] + lf[608 + r]), totB = (lf[640 + r] + lf[672 + r]) + (lf[704 + r] + lf[736 + r]);
;                 const float* gs = p.g_memo + 64 * wid + 4 * hh;
;                 store_head(a0, a1, rsqrtf(totA * (1.0f / 256.0f) + EPS), gl, r, 768 + 64 * wid + 4 * hh, gs, Y + (size_t)tqA * 1024 + 768 + 64 * wid + 4 * hh);
;                 store_head(b0, b1, rsqrtf(totB * (1.0f / 256.0f) + EPS), gl, r + 32, 768 + 64 * wid + 4 * hh, gs, Y + (size_t)tqB * 1024 + 768 + 64 * wid + 4 * hh);
.LBB0_440:
	s_andn2_b64 vcc, exec, s[0:1]
	s_cbranch_vccnz .LBB0_395
	v_add_u32_e32 v6, 0x800, v161
	ds_read2_b32 v[0:1], v6 offset1:32
	ds_read2_b32 v[2:3], v6 offset0:64 offset1:96
	ds_read2_b32 v[4:5], v6 offset0:128 offset1:160
	ds_read2_b32 v[6:7], v6 offset0:192 offset1:224
	v_add_u32_e32 v26, 0x330, v158
	s_waitcnt lgkmcnt(3)
	v_mov_b32_e32 v8, v0
	s_waitcnt lgkmcnt(2)
	v_mov_b32_e32 v9, v2
	v_mov_b32_e32 v2, v1
	s_waitcnt lgkmcnt(1)
	v_mov_b32_e32 v0, v4
	s_waitcnt lgkmcnt(0)
	v_mov_b32_e32 v1, v6
	v_mov_b32_e32 v6, v5
	v_pk_add_f32 v[36:37], v[0:1], v[6:7]
	v_add_u32_e32 v6, 0x310, v158
	v_lshlrev_b32_e32 v7, 1, v6
	v_lshrrev_b32_e32 v6, 3, v6
	v_bitop3_b32 v6, v6, v160, 63 bitop3:0x6c
	v_pk_add_f32 v[34:35], v[8:9], v[2:3]
	v_add_u32_e32 v0, 0x300, v158
	v_and_b32_e32 v8, 0xfffffc00, v7
	v_lshlrev_b32_e32 v6, 4, v6
	v_and_b32_e32 v120, 8, v7
	v_add_u32_e32 v7, 0x318, v158
	v_lshlrev_b32_e32 v1, 1, v0
	v_lshrrev_b32_e32 v0, 3, v0
	v_add3_u32 v121, 0, v6, v8
	v_lshlrev_b32_e32 v8, 1, v7
	v_lshrrev_b32_e32 v7, 3, v7
	v_bitop3_b32 v0, v0, v160, 63 bitop3:0x6c
	v_bitop3_b32 v7, v7, v160, 63 bitop3:0x6c
	v_and_b32_e32 v2, 0xfffffc00, v1
	v_lshlrev_b32_e32 v0, 4, v0
	v_and_b32_e32 v9, 0xfffffc00, v8
	v_lshlrev_b32_e32 v7, 4, v7
	v_and_b32_e32 v122, 8, v8
	v_add_u32_e32 v8, 0x320, v158
	v_add3_u32 v117, 0, v0, v2
	v_add_u32_e32 v0, 0x308, v158
	v_add3_u32 v123, 0, v7, v9
	v_lshlrev_b32_e32 v9, 1, v8
	v_lshrrev_b32_e32 v8, 3, v8
	v_and_b32_e32 v116, 8, v1
	v_lshlrev_b32_e32 v1, 1, v0
	v_lshrrev_b32_e32 v0, 3, v0
	v_bitop3_b32 v8, v8, v160, 63 bitop3:0x6c
	v_lshlrev_b32_e32 v27, 1, v26
	v_lshrrev_b32_e32 v26, 3, v26
	v_bitop3_b32 v0, v0, v160, 63 bitop3:0x6c
	v_and_b32_e32 v10, 0xfffffc00, v9
	v_lshlrev_b32_e32 v8, 4, v8
	v_bitop3_b32 v26, v26, v160, 63 bitop3:0x6c
	v_and_b32_e32 v2, 0xfffffc00, v1
	v_lshlrev_b32_e32 v0, 4, v0
	v_add3_u32 v155, 0, v8, v10
	v_add_u32_e32 v8, 0x328, v158
	v_and_b32_e32 v28, 0xfffffc00, v27
	v_lshlrev_b32_e32 v26, 4, v26
	v_and_b32_e32 v161, 8, v27
	v_add_u32_e32 v27, 0x338, v158
	v_lshl_add_u64 v[32:33], v[144:145], 2, s[60:61]
	v_add3_u32 v4, v117, v159, v116
	v_and_b32_e32 v118, 8, v1
	v_add3_u32 v119, 0, v0, v2
	v_and_b32_e32 v154, 8, v9
	v_lshlrev_b32_e32 v9, 1, v8
	v_lshrrev_b32_e32 v8, 3, v8
	v_add3_u32 v163, 0, v26, v28
	v_lshlrev_b32_e32 v28, 1, v27
	v_lshrrev_b32_e32 v27, 3, v27
	v_add3_u32 v5, v119, v159, v118
	global_load_dwordx4 v[12:15], v[32:33], off
	global_load_dwordx4 v[0:3], v[32:33], off offset:32
	v_add3_u32 v6, v121, v159, v120
	v_add3_u32 v7, v123, v159, v122
	ds_read_b64 v[38:39], v4 offset:4096
	ds_read_b64 v[108:109], v5 offset:4096
	ds_read_b64 v[114:115], v6 offset:4096
	ds_read_b64 v[124:125], v7 offset:4096
	v_bitop3_b32 v8, v8, v160, 63 bitop3:0x6c
	v_bitop3_b32 v27, v27, v160, 63 bitop3:0x6c
	v_and_b32_e32 v10, 0xfffffc00, v9
	v_lshlrev_b32_e32 v8, 4, v8
	v_and_b32_e32 v29, 0xfffffc00, v28
	v_lshlrev_b32_e32 v27, 4, v27
	v_add3_u32 v24, v155, v159, v154
	v_and_b32_e32 v156, 8, v9
	v_add3_u32 v157, 0, v8, v10
	v_and_b32_e32 v158, 8, v28
	v_add3_u32 v160, 0, v27, v29
	s_waitcnt lgkmcnt(3)
	v_lshlrev_b32_e32 v106, 16, v38
	global_load_dwordx4 v[16:19], v[32:33], off offset:64
	global_load_dwordx4 v[4:7], v[32:33], off offset:96
	v_add3_u32 v25, v157, v159, v156
	global_load_dwordx4 v[20:23], v[32:33], off offset:128
	global_load_dwordx4 v[8:11], v[32:33], off offset:160
	v_add3_u32 v26, v163, v159, v161
	v_add3_u32 v27, v160, v159, v158
	ds_read_b64 v[126:127], v24 offset:4096
	ds_read_b64 v[128:129], v25 offset:4096
	ds_read_b64 v[112:113], v26 offset:4096
	ds_read_b64 v[96:97], v27 offset:4096
	v_and_b32_e32 v107, 0xffff0000, v38
	v_mul_f32_e32 v24, 0xbfb8aa3b, v106
	v_exp_f32_e32 v38, v24
	v_mul_f32_e32 v24, 0xbfb8aa3b, v107
	v_exp_f32_e32 v111, v24
	v_lshlrev_b32_e32 v130, 16, v39
	v_add_f32_e32 v38, 1.0, v38
	v_rcp_f32_e32 v110, v38
	v_add_f32_e32 v38, 1.0, v111
	v_rcp_f32_e32 v111, v38
	v_and_b32_e32 v131, 0xffff0000, v39
	v_mul_f32_e32 v38, 0xbfb8aa3b, v130
	v_exp_f32_e32 v132, v38
	v_mul_f32_e32 v38, 0xbfb8aa3b, v131
	v_exp_f32_e32 v133, v38
	v_pk_mul_f32 v[38:39], v[110:111], v[106:107]
	s_waitcnt lgkmcnt(6)
	v_lshlrev_b32_e32 v110, 16, v108
	v_and_b32_e32 v111, 0xffff0000, v108
	v_mul_f32_e32 v108, 0xbfb8aa3b, v110
	v_add_f32_e32 v106, 1.0, v132
	v_add_f32_e32 v107, 1.0, v133
	v_exp_f32_e32 v108, v108
	v_mul_f32_e32 v132, 0xbfb8aa3b, v111
	v_rcp_f32_e32 v106, v106
	v_rcp_f32_e32 v107, v107
	v_exp_f32_e32 v132, v132
	v_add_f32_e32 v108, 1.0, v108
	v_and_b32_e32 v133, 0xffff0000, v109
	v_pk_mul_f32 v[106:107], v[106:107], v[130:131]
	v_rcp_f32_e32 v130, v108
	v_add_f32_e32 v108, 1.0, v132
	v_lshlrev_b32_e32 v132, 16, v109
	v_rcp_f32_e32 v131, v108
	v_mul_f32_e32 v108, 0xbfb8aa3b, v132
	v_exp_f32_e32 v134, v108
	v_mul_f32_e32 v108, 0xbfb8aa3b, v133
	v_exp_f32_e32 v135, v108
	v_pk_mul_f32 v[108:109], v[130:131], v[110:111]
	s_waitcnt lgkmcnt(5)
	v_lshlrev_b32_e32 v130, 16, v114
	v_and_b32_e32 v131, 0xffff0000, v114
	v_mul_f32_e32 v114, 0xbfb8aa3b, v130
	v_add_f32_e32 v110, 1.0, v134
	v_add_f32_e32 v111, 1.0, v135
	v_exp_f32_e32 v114, v114
	v_mul_f32_e32 v134, 0xbfb8aa3b, v131
	v_rcp_f32_e32 v110, v110
	v_rcp_f32_e32 v111, v111
	v_exp_f32_e32 v134, v134
	v_add_f32_e32 v114, 1.0, v114
	v_and_b32_e32 v135, 0xffff0000, v115
	v_pk_mul_f32 v[110:111], v[110:111], v[132:133]
	v_rcp_f32_e32 v132, v114
	v_add_f32_e32 v114, 1.0, v134
	v_lshlrev_b32_e32 v134, 16, v115
	v_rcp_f32_e32 v133, v114
	v_mul_f32_e32 v114, 0xbfb8aa3b, v134
	v_exp_f32_e32 v136, v114
	v_mul_f32_e32 v114, 0xbfb8aa3b, v135
	v_exp_f32_e32 v137, v114
	v_pk_mul_f32 v[114:115], v[132:133], v[130:131]
	s_waitcnt lgkmcnt(4)
; DI unsigned pk_bf16(float lo, float hi) { f32x2 v = {lo, hi}; bf2_t b = __builtin_convertvector(v, bf2_t); return __builtin_bit_cast(unsigned, b); }
; DI float bf_lo(unsigned u) { return __uint_as_float(u << 16); }
; DI float bf_hi(unsigned u) { return __uint_as_float(u & 0xffff0000u); }
; DI float silu(float x) { return x * __builtin_amdgcn_rcpf(1.0f + __builtin_amdgcn_exp2f(-1.4426950408889634f * x)); }
; DI void store_head(const f32x16& o0, const f32x16& o1, float rs, const unsigned char* gl, int tr, int ch0, const float* gs, bf16_t* yp) {
;     u32x2 gt[8]; f32x4 gv[8];
; #pragma unroll
;     for (int q = 0; q < 8; ++q) { const int d = 32 * (q >> 2) + 8 * (q & 3); gt[q] = *(const u32x2*)(gl + gate_off(tr, ch0 + d)); gv[q] = *(const f32x4*)(gs + d); }
; #pragma unroll
;     for (int q = 0; q < 8; ++q) { const int d = 32 * (q >> 2) + 8 * (q & 3), g = q & 3;
;         const f32x16& o = (q >> 2) ? o1 : o0;
;         u32x2 w; w.x = pk_bf16(o[4 * g + 0] * rs * gv[q][0] * silu(bf_lo(gt[q].x)), o[4 * g + 1] * rs * gv[q][1] * silu(bf_hi(gt[q].x)));
;         w.y = pk_bf16(o[4 * g + 2] * rs * gv[q][2] * silu(bf_lo(gt[q].y)), o[4 * g + 3] * rs * gv[q][3] * silu(bf_hi(gt[q].y)));
;         *(u32x2*)(yp + d) = w; }
; }
; DI void mixer_phase(const Params& p, unsigned char* ldsraw, int vid) {
;     ...
;                 store_head(a0, a1, rsqrtf(totA * (1.0f / 256.0f) + EPS), gl, r, 768 + 64 * wid + 4 * hh, gs, Y + (size_t)tqA * 1024 + 768 + 64 * wid + 4 * hh);
	v_lshlrev_b32_e32 v132, 16, v124
	v_and_b32_e32 v133, 0xffff0000, v124
	v_mul_f32_e32 v124, 0xbfb8aa3b, v132
	v_add_f32_e32 v130, 1.0, v136
	v_add_f32_e32 v131, 1.0, v137
	v_exp_f32_e32 v124, v124
	v_mul_f32_e32 v136, 0xbfb8aa3b, v133
	v_rcp_f32_e32 v130, v130
	v_rcp_f32_e32 v131, v131
	v_exp_f32_e32 v136, v136
	v_add_f32_e32 v124, 1.0, v124
	global_load_dwordx4 v[28:31], v[32:33], off offset:192
	global_load_dwordx4 v[24:27], v[32:33], off offset:224
	v_pk_mul_f32 v[130:131], v[130:131], v[134:135]
	v_rcp_f32_e32 v134, v124
	v_add_f32_e32 v124, 1.0, v136
	v_rcp_f32_e32 v135, v124
	v_lshlrev_b32_e32 v124, 16, v125
	v_and_b32_e32 v125, 0xffff0000, v125
	v_mul_f32_e32 v136, 0xbfb8aa3b, v124
	v_exp_f32_e32 v136, v136
	v_mul_f32_e32 v137, 0xbfb8aa3b, v125
	v_exp_f32_e32 v137, v137
	v_pk_mul_f32 v[132:133], v[134:135], v[132:133]
	v_add_f32_e32 v134, 1.0, v136
	s_waitcnt lgkmcnt(3)
	v_lshlrev_b32_e32 v136, 16, v126
	v_add_f32_e32 v135, 1.0, v137
	v_and_b32_e32 v137, 0xffff0000, v126
	v_mul_f32_e32 v126, 0xbfb8aa3b, v136
	v_exp_f32_e32 v126, v126
	v_mul_f32_e32 v138, 0xbfb8aa3b, v137
	v_rcp_f32_e32 v134, v134
	v_rcp_f32_e32 v135, v135
	v_exp_f32_e32 v138, v138
	v_add_f32_e32 v126, 1.0, v126
	s_waitcnt lgkmcnt(0)
	v_and_b32_e32 v149, 0xffff0000, v97
	v_pk_mul_f32 v[124:125], v[134:135], v[124:125]
	v_rcp_f32_e32 v134, v126
	v_add_f32_e32 v126, 1.0, v138
	v_rcp_f32_e32 v135, v126
	v_lshlrev_b32_e32 v126, 16, v127
	v_and_b32_e32 v127, 0xffff0000, v127
	v_mul_f32_e32 v138, 0xbfb8aa3b, v126
	v_exp_f32_e32 v138, v138
	v_mul_f32_e32 v139, 0xbfb8aa3b, v127
	v_exp_f32_e32 v139, v139
	v_pk_mul_f32 v[134:135], v[134:135], v[136:137]
	v_add_f32_e32 v136, 1.0, v138
	v_lshlrev_b32_e32 v138, 16, v128
	v_add_f32_e32 v137, 1.0, v139
	v_and_b32_e32 v139, 0xffff0000, v128
	v_mul_f32_e32 v128, 0xbfb8aa3b, v138
	v_exp_f32_e32 v128, v128
	v_mul_f32_e32 v144, 0xbfb8aa3b, v139
	v_rcp_f32_e32 v136, v136
	v_rcp_f32_e32 v137, v137
	v_exp_f32_e32 v144, v144
	v_add_f32_e32 v128, 1.0, v128
	v_mov_b32_e32 v153, v34
	v_pk_mul_f32 v[126:127], v[136:137], v[126:127]
	v_rcp_f32_e32 v136, v128
	v_add_f32_e32 v128, 1.0, v144
	v_rcp_f32_e32 v137, v128
	v_lshlrev_b32_e32 v128, 16, v129
	v_and_b32_e32 v129, 0xffff0000, v129
	v_mul_f32_e32 v144, 0xbfb8aa3b, v128
	v_exp_f32_e32 v144, v144
	v_mul_f32_e32 v145, 0xbfb8aa3b, v129
	v_exp_f32_e32 v145, v145
	v_pk_mul_f32 v[136:137], v[136:137], v[138:139]
	v_add_f32_e32 v138, 1.0, v144
	v_lshlrev_b32_e32 v144, 16, v112
	v_add_f32_e32 v139, 1.0, v145
	v_and_b32_e32 v145, 0xffff0000, v112
	v_mul_f32_e32 v112, 0xbfb8aa3b, v144
	v_exp_f32_e32 v112, v112
	v_mul_f32_e32 v146, 0xbfb8aa3b, v145
	v_rcp_f32_e32 v138, v138
	v_rcp_f32_e32 v139, v139
	v_exp_f32_e32 v146, v146
	v_add_f32_e32 v112, 1.0, v112
	v_mov_b32_e32 v34, v37
	v_pk_mul_f32 v[128:129], v[138:139], v[128:129]
	v_rcp_f32_e32 v138, v112
	v_add_f32_e32 v112, 1.0, v146
	v_rcp_f32_e32 v139, v112
	v_lshlrev_b32_e32 v112, 16, v113
	v_and_b32_e32 v113, 0xffff0000, v113
	v_mul_f32_e32 v147, 0xbfb8aa3b, v113
	v_exp_f32_e32 v147, v147
	v_pk_mul_f32 v[138:139], v[138:139], v[144:145]
	v_mul_f32_e32 v146, 0xbfb8aa3b, v112
	v_exp_f32_e32 v146, v146
	v_add_f32_e32 v145, 1.0, v147
	v_and_b32_e32 v147, 0xffff0000, v96
	v_mul_f32_e32 v148, 0xbfb8aa3b, v147
	v_exp_f32_e32 v148, v148
	v_add_f32_e32 v144, 1.0, v146
	v_rcp_f32_e32 v144, v144
	v_rcp_f32_e32 v145, v145
	v_add_f32_e32 v150, 1.0, v148
	v_lshlrev_b32_e32 v148, 16, v97
	v_mul_f32_e32 v97, 0xbfb8aa3b, v148
	v_exp_f32_e32 v151, v97
	v_mul_f32_e32 v97, 0xbfb8aa3b, v149
	v_exp_f32_e32 v152, v97
	v_rcp_f32_e32 v97, v150
	v_add_f32_e32 v150, 1.0, v151
	v_lshlrev_b32_e32 v146, 16, v96
	v_add_f32_e32 v151, 1.0, v152
	v_mov_b32_e32 v152, v36
	v_pk_add_f32 v[34:35], v[152:153], v[34:35]
	v_mul_f32_e32 v96, 0xbfb8aa3b, v146
	v_pk_fma_f32 v[34:35], v[34:35], s[88:89], v[178:179] op_sel_hi:[1,0,0]
	v_exp_f32_e32 v96, v96
	v_mul_f32_e32 v36, 0x4b800000, v35
	v_cmp_gt_f32_e32 vcc, s98, v35
	v_rcp_f32_e32 v150, v150
	v_add_f32_e32 v96, 1.0, v96
	v_cndmask_b32_e32 v35, v35, v36, vcc
	v_rsq_f32_e32 v35, v35
	v_pk_mul_f32 v[36:37], v[144:145], v[112:113]
	v_rcp_f32_e32 v96, v96
	v_rcp_f32_e32 v151, v151
	v_mul_f32_e32 v144, 0x45800000, v35
	v_cndmask_b32_e32 v144, v35, v144, vcc
	v_pk_mul_f32 v[48:49], v[48:49], v[144:145] op_sel_hi:[1,0]
	v_pk_mul_f32 v[96:97], v[96:97], v[146:147]
	s_waitcnt vmcnt(7)
	v_pk_mul_f32 v[12:13], v[12:13], v[48:49]
	v_pk_mul_f32 v[112:113], v[150:151], v[148:149]
	v_pk_mul_f32 v[12:13], v[12:13], v[38:39]
	v_pk_mul_f32 v[38:39], v[50:51], v[144:145] op_sel_hi:[1,0]
	v_cvt_pk_bf16_f32 v236, v12, v13
	v_pk_mul_f32 v[14:15], v[14:15], v[38:39]
	v_cmp_gt_f32_e32 vcc, s98, v34
	v_pk_mul_f32 v[14:15], v[14:15], v[106:107]
	s_nop 0
	v_cvt_pk_bf16_f32 v237, v14, v15
	v_and_b32_e32 v252, 32, v205
	v_lshrrev_b32_e32 v252, 2, v252
	v_mov_b32_e32 v253, 0
	v_lshl_add_u64 v[254:255], v[140:141], 0, v[252:253]
	v_pk_mul_f32 v[12:13], v[52:53], v[144:145] op_sel_hi:[1,0]
	s_waitcnt vmcnt(6)
	v_pk_mul_f32 v[0:1], v[0:1], v[12:13]
	v_pk_mul_f32 v[12:13], v[54:55], v[144:145] op_sel_hi:[1,0]
	v_pk_mul_f32 v[0:1], v[0:1], v[108:109]
	v_pk_mul_f32 v[2:3], v[2:3], v[12:13]
	v_cvt_pk_bf16_f32 v238, v0, v1
	v_pk_mul_f32 v[2:3], v[2:3], v[110:111]
	s_nop 0
	v_cvt_pk_bf16_f32 v239, v2, v3
	s_nop 1
	v_permlane32_swap_b32_e32 v236, v238
	v_permlane32_swap_b32_e32 v237, v239
	global_store_dwordx4 v[254:255], v[236:239], off offset:1536
	v_pk_mul_f32 v[0:1], v[56:57], v[144:145] op_sel_hi:[1,0]
	v_pk_mul_f32 v[2:3], v[40:41], v[144:145] op_sel_hi:[1,0]
	s_waitcnt vmcnt(6)
; DI unsigned pk_bf16(float lo, float hi) { f32x2 v = {lo, hi}; bf2_t b = __builtin_convertvector(v, bf2_t); return __builtin_bit_cast(unsigned, b); }
; DI float bf_lo(unsigned u) { return __uint_as_float(u << 16); }
; DI float bf_hi(unsigned u) { return __uint_as_float(u & 0xffff0000u); }
; DI float silu(float x) { return x * __builtin_amdgcn_rcpf(1.0f + __builtin_amdgcn_exp2f(-1.4426950408889634f * x)); }
; DI void store_head(const f32x16& o0, const f32x16& o1, float rs, const unsigned char* gl, int tr, int ch0, const float* gs, bf16_t* yp) {
;     u32x2 gt[8]; f32x4 gv[8];
; #pragma unroll
;     for (int q = 0; q < 8; ++q) { const int d = 32 * (q >> 2) + 8 * (q & 3); gt[q] = *(const u32x2*)(gl + gate_off(tr, ch0 + d)); gv[q] = *(const f32x4*)(gs + d); }
; #pragma unroll
;     for (int q = 0; q < 8; ++q) { const int d = 32 * (q >> 2) + 8 * (q & 3), g = q & 3;
;         const f32x16& o = (q >> 2) ? o1 : o0;
;         u32x2 w; w.x = pk_bf16(o[4 * g + 0] * rs * gv[q][0] * silu(bf_lo(gt[q].x)), o[4 * g + 1] * rs * gv[q][1] * silu(bf_hi(gt[q].x)));
;         w.y = pk_bf16(o[4 * g + 2] * rs * gv[q][2] * silu(bf_lo(gt[q].y)), o[4 * g + 3] * rs * gv[q][3] * silu(bf_hi(gt[q].y)));
;         *(u32x2*)(yp + d) = w; }
; }
; DI void mixer_phase(const Params& p, unsigned char* ldsraw, int vid) {
;     ...
;                 store_head(a0, a1, rsqrtf(totA * (1.0f / 256.0f) + EPS), gl, r, 768 + 64 * wid + 4 * hh, gs, Y + (size_t)tqA * 1024 + 768 + 64 * wid + 4 * hh);
;                 store_head(b0, b1, rsqrtf(totB * (1.0f / 256.0f) + EPS), gl, r + 32, 768 + 64 * wid + 4 * hh, gs, Y + (size_t)tqB * 1024 + 768 + 64 * wid + 4 * hh);
	v_pk_mul_f32 v[0:1], v[0:1], v[16:17]
	v_pk_mul_f32 v[2:3], v[2:3], v[18:19]
	v_pk_mul_f32 v[0:1], v[0:1], v[114:115]
	v_pk_mul_f32 v[2:3], v[2:3], v[130:131]
	v_cvt_pk_bf16_f32 v240, v0, v1
	v_cvt_pk_bf16_f32 v241, v2, v3
	v_pk_mul_f32 v[0:1], v[42:43], v[144:145] op_sel_hi:[1,0]
	v_pk_mul_f32 v[2:3], v[44:45], v[144:145] op_sel_hi:[1,0]
	s_waitcnt vmcnt(5)
	v_pk_mul_f32 v[0:1], v[0:1], v[4:5]
	v_pk_mul_f32 v[2:3], v[2:3], v[6:7]
	v_pk_mul_f32 v[0:1], v[0:1], v[132:133]
	v_pk_mul_f32 v[2:3], v[2:3], v[124:125]
	v_cvt_pk_bf16_f32 v242, v0, v1
	v_cvt_pk_bf16_f32 v243, v2, v3
	s_nop 1
	v_permlane32_swap_b32_e32 v240, v242
	v_permlane32_swap_b32_e32 v241, v243
	global_store_dwordx4 v[254:255], v[240:243], off offset:1568
	v_pk_mul_f32 v[0:1], v[64:65], v[144:145] op_sel_hi:[1,0]
	v_pk_mul_f32 v[2:3], v[66:67], v[144:145] op_sel_hi:[1,0]
	s_waitcnt vmcnt(5)
	v_pk_mul_f32 v[0:1], v[0:1], v[20:21]
	v_pk_mul_f32 v[2:3], v[2:3], v[22:23]
	v_pk_mul_f32 v[0:1], v[0:1], v[134:135]
	v_pk_mul_f32 v[2:3], v[2:3], v[126:127]
	v_cvt_pk_bf16_f32 v244, v0, v1
	v_cvt_pk_bf16_f32 v245, v2, v3
	v_pk_mul_f32 v[0:1], v[68:69], v[144:145] op_sel_hi:[1,0]
	v_pk_mul_f32 v[2:3], v[70:71], v[144:145] op_sel_hi:[1,0]
	s_waitcnt vmcnt(4)
	v_pk_mul_f32 v[0:1], v[0:1], v[8:9]
	v_pk_mul_f32 v[2:3], v[2:3], v[10:11]
	v_pk_mul_f32 v[0:1], v[0:1], v[136:137]
	v_pk_mul_f32 v[2:3], v[2:3], v[128:129]
	v_cvt_pk_bf16_f32 v246, v0, v1
	v_cvt_pk_bf16_f32 v247, v2, v3
	s_nop 1
	v_permlane32_swap_b32_e32 v244, v246
	v_permlane32_swap_b32_e32 v245, v247
	global_store_dwordx4 v[254:255], v[244:247], off offset:1600
	v_pk_mul_f32 v[0:1], v[72:73], v[144:145] op_sel_hi:[1,0]
	v_pk_mul_f32 v[2:3], v[58:59], v[144:145] op_sel_hi:[1,0]
	s_waitcnt vmcnt(4)
	v_pk_mul_f32 v[0:1], v[0:1], v[28:29]
	v_pk_mul_f32 v[2:3], v[2:3], v[30:31]
	v_pk_mul_f32 v[0:1], v[0:1], v[138:139]
	v_pk_mul_f32 v[2:3], v[2:3], v[36:37]
	v_cvt_pk_bf16_f32 v248, v0, v1
	v_cvt_pk_bf16_f32 v249, v2, v3
	v_pk_mul_f32 v[0:1], v[60:61], v[144:145] op_sel_hi:[1,0]
	v_pk_mul_f32 v[2:3], v[46:47], v[144:145] op_sel_hi:[1,0]
	s_waitcnt vmcnt(3)
	v_pk_mul_f32 v[0:1], v[0:1], v[24:25]
	v_pk_mul_f32 v[2:3], v[2:3], v[26:27]
	v_pk_mul_f32 v[0:1], v[0:1], v[96:97]
	v_pk_mul_f32 v[2:3], v[2:3], v[112:113]
	v_cvt_pk_bf16_f32 v250, v0, v1
	v_cvt_pk_bf16_f32 v251, v2, v3
	s_nop 1
	v_permlane32_swap_b32_e32 v248, v250
	v_permlane32_swap_b32_e32 v249, v251
	global_store_dwordx4 v[254:255], v[248:251], off offset:1632
	global_load_dwordx4 v[24:27], v[32:33], off
	global_load_dwordx4 v[28:31], v[32:33], off offset:32
	v_mul_f32_e32 v0, 0x4b800000, v34
	v_cndmask_b32_e32 v0, v34, v0, vcc
	v_rsq_f32_e32 v0, v0
	v_add3_u32 v2, v121, v162, v120
	v_add3_u32 v3, v123, v162, v122
	v_mul_f32_e32 v1, 0x45800000, v0
	v_cndmask_b32_e32 v16, v0, v1, vcc
	v_add3_u32 v0, v117, v162, v116
	v_add3_u32 v1, v119, v162, v118
	ds_read_b64 v[42:43], v0 offset:4096
	ds_read_b64 v[44:45], v1 offset:4096
	ds_read_b64 v[46:47], v2 offset:4096
	ds_read_b64 v[48:49], v3 offset:4096
	global_load_dwordx4 v[34:37], v[32:33], off offset:64
	global_load_dwordx4 v[38:41], v[32:33], off offset:96
	s_waitcnt lgkmcnt(3)
	v_lshlrev_b32_e32 v50, 16, v42
	v_and_b32_e32 v51, 0xffff0000, v42
	v_mul_f32_e32 v4, 0xbfb8aa3b, v50
	v_exp_f32_e32 v4, v4
	v_mul_f32_e32 v5, 0xbfb8aa3b, v51
	v_exp_f32_e32 v5, v5
	v_add3_u32 v0, v155, v162, v154
	v_add3_u32 v1, v157, v162, v156
	global_load_dwordx4 v[12:15], v[32:33], off offset:128
	global_load_dwordx4 v[8:11], v[32:33], off offset:160
	v_add3_u32 v2, v163, v162, v161
	v_add3_u32 v3, v160, v162, v158
	ds_read_b64 v[52:53], v0 offset:4096
	ds_read_b64 v[22:23], v1 offset:4096
	ds_read_b64 v[20:21], v2 offset:4096
	ds_read_b64 v[18:19], v3 offset:4096
	v_add_f32_e32 v0, 1.0, v4
	v_rcp_f32_e32 v54, v0
	v_add_f32_e32 v0, 1.0, v5
	v_rcp_f32_e32 v55, v0
	v_lshlrev_b32_e32 v42, 16, v43
	global_load_dwordx4 v[4:7], v[32:33], off offset:192
	global_load_dwordx4 v[0:3], v[32:33], off offset:224
	v_pk_mul_f32 v[32:33], v[80:81], v[16:17] op_sel_hi:[1,0]
	v_and_b32_e32 v43, 0xffff0000, v43
	v_mul_f32_e32 v17, 0xbfb8aa3b, v42
	v_exp_f32_e32 v17, v17
	s_waitcnt vmcnt(7)
	v_pk_mul_f32 v[24:25], v[32:33], v[24:25]
	v_pk_mul_f32 v[32:33], v[54:55], v[50:51]
	v_mul_f32_e32 v50, 0xbfb8aa3b, v43
	v_exp_f32_e32 v50, v50
	v_add_f32_e32 v17, 1.0, v17
	v_pk_mul_f32 v[24:25], v[24:25], v[32:33]
	v_rcp_f32_e32 v32, v17
	v_add_f32_e32 v17, 1.0, v50
	v_rcp_f32_e32 v33, v17
	v_pk_mul_f32 v[50:51], v[76:77], v[16:17] op_sel_hi:[1,0]
	v_cvt_pk_bf16_f32 v236, v24, v25
	v_pk_mul_f32 v[26:27], v[50:51], v[26:27]
	v_pk_mul_f32 v[32:33], v[32:33], v[42:43]
	s_nop 0
	v_pk_mul_f32 v[26:27], v[26:27], v[32:33]
	s_waitcnt lgkmcnt(6)
	v_lshlrev_b32_e32 v32, 16, v44
	v_and_b32_e32 v33, 0xffff0000, v44
	v_mul_f32_e32 v17, 0xbfb8aa3b, v32
	v_exp_f32_e32 v17, v17
	v_mul_f32_e32 v25, 0xbfb8aa3b, v33
	v_exp_f32_e32 v42, v25
	v_cvt_pk_bf16_f32 v237, v26, v27
	v_add_f32_e32 v17, 1.0, v17
	v_rcp_f32_e32 v26, v17
	v_add_f32_e32 v17, 1.0, v42
	v_rcp_f32_e32 v27, v17
	v_and_b32_e32 v252, 32, v205
	v_lshrrev_b32_e32 v252, 2, v252
	v_mov_b32_e32 v253, 0
	v_lshl_add_u64 v[254:255], v[142:143], 0, v[252:253]
	v_pk_mul_f32 v[24:25], v[74:75], v[16:17] op_sel_hi:[1,0]
	v_pk_mul_f32 v[26:27], v[26:27], v[32:33]
	s_waitcnt vmcnt(6)
	v_pk_mul_f32 v[24:25], v[24:25], v[28:29]
	v_lshlrev_b32_e32 v28, 16, v45
	v_and_b32_e32 v29, 0xffff0000, v45
	v_mul_f32_e32 v17, 0xbfb8aa3b, v28
	v_exp_f32_e32 v17, v17
	v_mul_f32_e32 v32, 0xbfb8aa3b, v29
	v_exp_f32_e32 v32, v32
	v_pk_mul_f32 v[24:25], v[24:25], v[26:27]
	v_add_f32_e32 v17, 1.0, v17
	v_rcp_f32_e32 v26, v17
	v_add_f32_e32 v17, 1.0, v32
	v_rcp_f32_e32 v27, v17
	v_pk_mul_f32 v[32:33], v[78:79], v[16:17] op_sel_hi:[1,0]
	v_cvt_pk_bf16_f32 v238, v24, v25
	v_pk_mul_f32 v[30:31], v[32:33], v[30:31]
	v_pk_mul_f32 v[26:27], v[26:27], v[28:29]
	s_waitcnt lgkmcnt(5)
; DI unsigned pk_bf16(float lo, float hi) { f32x2 v = {lo, hi}; bf2_t b = __builtin_convertvector(v, bf2_t); return __builtin_bit_cast(unsigned, b); }
; DI float bf_lo(unsigned u) { return __uint_as_float(u << 16); }
; DI float bf_hi(unsigned u) { return __uint_as_float(u & 0xffff0000u); }
; DI float silu(float x) { return x * __builtin_amdgcn_rcpf(1.0f + __builtin_amdgcn_exp2f(-1.4426950408889634f * x)); }
; DI void store_head(const f32x16& o0, const f32x16& o1, float rs, const unsigned char* gl, int tr, int ch0, const float* gs, bf16_t* yp) {
;     u32x2 gt[8]; f32x4 gv[8];
; #pragma unroll
;     for (int q = 0; q < 8; ++q) { const int d = 32 * (q >> 2) + 8 * (q & 3); gt[q] = *(const u32x2*)(gl + gate_off(tr, ch0 + d)); gv[q] = *(const f32x4*)(gs + d); }
; #pragma unroll
;     for (int q = 0; q < 8; ++q) { const int d = 32 * (q >> 2) + 8 * (q & 3), g = q & 3;
;         const f32x16& o = (q >> 2) ? o1 : o0;
;         u32x2 w; w.x = pk_bf16(o[4 * g + 0] * rs * gv[q][0] * silu(bf_lo(gt[q].x)), o[4 * g + 1] * rs * gv[q][1] * silu(bf_hi(gt[q].x)));
;         w.y = pk_bf16(o[4 * g + 2] * rs * gv[q][2] * silu(bf_lo(gt[q].y)), o[4 * g + 3] * rs * gv[q][3] * silu(bf_hi(gt[q].y)));
;         *(u32x2*)(yp + d) = w; }
; }
	v_lshlrev_b32_e32 v28, 16, v46
	v_and_b32_e32 v29, 0xffff0000, v46
	v_mul_f32_e32 v17, 0xbfb8aa3b, v28
	v_exp_f32_e32 v17, v17
	v_mul_f32_e32 v25, 0xbfb8aa3b, v29
	v_pk_mul_f32 v[26:27], v[30:31], v[26:27]
	v_exp_f32_e32 v30, v25
	v_add_f32_e32 v17, 1.0, v17
	v_cvt_pk_bf16_f32 v239, v26, v27
	v_rcp_f32_e32 v26, v17
	v_add_f32_e32 v17, 1.0, v30
	v_rcp_f32_e32 v27, v17
	s_nop 1
	v_permlane32_swap_b32_e32 v236, v238
	v_permlane32_swap_b32_e32 v237, v239
	global_store_dwordx4 v[254:255], v[236:239], off offset:1536
	v_pk_mul_f32 v[24:25], v[86:87], v[16:17] op_sel_hi:[1,0]
	v_pk_mul_f32 v[26:27], v[26:27], v[28:29]
	v_lshlrev_b32_e32 v28, 16, v47
	v_and_b32_e32 v29, 0xffff0000, v47
	v_mul_f32_e32 v17, 0xbfb8aa3b, v28
	v_exp_f32_e32 v17, v17
	v_mul_f32_e32 v30, 0xbfb8aa3b, v29
	v_exp_f32_e32 v30, v30
	s_waitcnt vmcnt(6)
	v_pk_mul_f32 v[24:25], v[24:25], v[34:35]
	v_add_f32_e32 v17, 1.0, v17
	v_pk_mul_f32 v[24:25], v[24:25], v[26:27]
	v_rcp_f32_e32 v26, v17
	v_add_f32_e32 v17, 1.0, v30
	v_rcp_f32_e32 v27, v17
	v_pk_mul_f32 v[30:31], v[84:85], v[16:17] op_sel_hi:[1,0]
	v_cvt_pk_bf16_f32 v240, v24, v25
	v_pk_mul_f32 v[30:31], v[30:31], v[36:37]
	v_pk_mul_f32 v[26:27], v[26:27], v[28:29]
	s_waitcnt lgkmcnt(4)
	v_lshlrev_b32_e32 v28, 16, v48
	v_and_b32_e32 v29, 0xffff0000, v48
	v_mul_f32_e32 v17, 0xbfb8aa3b, v28
	v_exp_f32_e32 v17, v17
	v_mul_f32_e32 v25, 0xbfb8aa3b, v29
	v_pk_mul_f32 v[26:27], v[30:31], v[26:27]
	v_exp_f32_e32 v30, v25
	v_add_f32_e32 v17, 1.0, v17
	v_cvt_pk_bf16_f32 v241, v26, v27
	v_rcp_f32_e32 v26, v17
	v_add_f32_e32 v17, 1.0, v30
	v_rcp_f32_e32 v27, v17
	v_pk_mul_f32 v[24:25], v[82:83], v[16:17] op_sel_hi:[1,0]
	v_pk_mul_f32 v[26:27], v[26:27], v[28:29]
	v_lshlrev_b32_e32 v28, 16, v49
	v_and_b32_e32 v29, 0xffff0000, v49
	v_mul_f32_e32 v17, 0xbfb8aa3b, v28
	v_exp_f32_e32 v17, v17
	v_mul_f32_e32 v30, 0xbfb8aa3b, v29
	v_exp_f32_e32 v30, v30
	s_waitcnt vmcnt(5)
	v_pk_mul_f32 v[24:25], v[24:25], v[38:39]
	v_add_f32_e32 v17, 1.0, v17
	v_pk_mul_f32 v[24:25], v[24:25], v[26:27]
	v_rcp_f32_e32 v26, v17
	v_add_f32_e32 v17, 1.0, v30
	v_rcp_f32_e32 v27, v17
	v_pk_mul_f32 v[30:31], v[62:63], v[16:17] op_sel_hi:[1,0]
	v_cvt_pk_bf16_f32 v242, v24, v25
	v_pk_mul_f32 v[30:31], v[30:31], v[40:41]
	v_pk_mul_f32 v[26:27], v[26:27], v[28:29]
	s_waitcnt lgkmcnt(3)
	v_lshlrev_b32_e32 v28, 16, v52
	v_and_b32_e32 v29, 0xffff0000, v52
	v_mul_f32_e32 v17, 0xbfb8aa3b, v28
	v_exp_f32_e32 v17, v17
	v_mul_f32_e32 v25, 0xbfb8aa3b, v29
	v_pk_mul_f32 v[26:27], v[30:31], v[26:27]
	v_exp_f32_e32 v30, v25
	v_add_f32_e32 v17, 1.0, v17
	v_cvt_pk_bf16_f32 v243, v26, v27
	v_rcp_f32_e32 v26, v17
	v_add_f32_e32 v17, 1.0, v30
	v_rcp_f32_e32 v27, v17
	s_nop 1
	v_permlane32_swap_b32_e32 v240, v242
	v_permlane32_swap_b32_e32 v241, v243
	global_store_dwordx4 v[254:255], v[240:243], off offset:1568
	v_pk_mul_f32 v[24:25], v[94:95], v[16:17] op_sel_hi:[1,0]
	s_waitcnt vmcnt(5)
	v_pk_mul_f32 v[12:13], v[24:25], v[12:13]
	v_pk_mul_f32 v[24:25], v[26:27], v[28:29]
	v_lshlrev_b32_e32 v26, 16, v53
	v_and_b32_e32 v27, 0xffff0000, v53
	v_mul_f32_e32 v17, 0xbfb8aa3b, v26
	v_exp_f32_e32 v17, v17
	v_mul_f32_e32 v28, 0xbfb8aa3b, v27
	v_exp_f32_e32 v28, v28
	v_pk_mul_f32 v[12:13], v[12:13], v[24:25]
	v_add_f32_e32 v17, 1.0, v17
	v_rcp_f32_e32 v24, v17
	v_add_f32_e32 v17, 1.0, v28
	v_rcp_f32_e32 v25, v17
	v_pk_mul_f32 v[28:29], v[90:91], v[16:17] op_sel_hi:[1,0]
	v_cvt_pk_bf16_f32 v244, v12, v13
	v_pk_mul_f32 v[14:15], v[28:29], v[14:15]
	v_pk_mul_f32 v[24:25], v[24:25], v[26:27]
	s_nop 0
	v_pk_mul_f32 v[14:15], v[14:15], v[24:25]
	s_waitcnt lgkmcnt(2)
	v_lshlrev_b32_e32 v24, 16, v22
	v_and_b32_e32 v25, 0xffff0000, v22
	v_mul_f32_e32 v13, 0xbfb8aa3b, v24
	v_exp_f32_e32 v17, v13
	v_mul_f32_e32 v13, 0xbfb8aa3b, v25
	v_exp_f32_e32 v22, v13
	v_cvt_pk_bf16_f32 v245, v14, v15
	v_add_f32_e32 v14, 1.0, v17
	v_rcp_f32_e32 v14, v14
	v_add_f32_e32 v15, 1.0, v22
	v_rcp_f32_e32 v15, v15
	v_pk_mul_f32 v[12:13], v[88:89], v[16:17] op_sel_hi:[1,0]
	s_waitcnt vmcnt(4)
	v_pk_mul_f32 v[8:9], v[12:13], v[8:9]
	v_pk_mul_f32 v[12:13], v[14:15], v[24:25]
	v_lshlrev_b32_e32 v14, 16, v23
	v_and_b32_e32 v15, 0xffff0000, v23
	v_mul_f32_e32 v17, 0xbfb8aa3b, v14
	v_mul_f32_e32 v22, 0xbfb8aa3b, v15
	v_exp_f32_e32 v17, v17
	v_exp_f32_e32 v22, v22
	v_pk_mul_f32 v[8:9], v[8:9], v[12:13]
	v_add_f32_e32 v12, 1.0, v17
	v_add_f32_e32 v13, 1.0, v22
	v_rcp_f32_e32 v12, v12
	v_rcp_f32_e32 v13, v13
	v_pk_mul_f32 v[22:23], v[92:93], v[16:17] op_sel_hi:[1,0]
	v_cvt_pk_bf16_f32 v246, v8, v9
	v_pk_mul_f32 v[10:11], v[22:23], v[10:11]
	v_pk_mul_f32 v[12:13], v[12:13], v[14:15]
	s_nop 0
	v_pk_mul_f32 v[10:11], v[10:11], v[12:13]
	s_waitcnt lgkmcnt(1)
	v_lshlrev_b32_e32 v12, 16, v20
	v_and_b32_e32 v13, 0xffff0000, v20
	v_mul_f32_e32 v9, 0xbfb8aa3b, v12
	v_exp_f32_e32 v14, v9
	v_mul_f32_e32 v9, 0xbfb8aa3b, v13
	v_exp_f32_e32 v15, v9
	v_cvt_pk_bf16_f32 v247, v10, v11
	v_add_f32_e32 v10, 1.0, v14
	v_rcp_f32_e32 v10, v10
	v_add_f32_e32 v11, 1.0, v15
	v_rcp_f32_e32 v11, v11
	s_nop 1
	v_permlane32_swap_b32_e32 v244, v246
	v_permlane32_swap_b32_e32 v245, v247
	global_store_dwordx4 v[254:255], v[244:247], off offset:1600
	v_pk_mul_f32 v[8:9], v[102:103], v[16:17] op_sel_hi:[1,0]
	s_waitcnt vmcnt(4)
	v_pk_mul_f32 v[4:5], v[8:9], v[4:5]
	v_pk_mul_f32 v[8:9], v[10:11], v[12:13]
	v_lshlrev_b32_e32 v10, 16, v21
	v_and_b32_e32 v11, 0xffff0000, v21
	v_mul_f32_e32 v12, 0xbfb8aa3b, v10
	v_mul_f32_e32 v13, 0xbfb8aa3b, v11
	v_exp_f32_e32 v12, v12
	v_exp_f32_e32 v13, v13
	v_pk_mul_f32 v[4:5], v[4:5], v[8:9]
	v_add_f32_e32 v8, 1.0, v12
	v_add_f32_e32 v9, 1.0, v13
	v_rcp_f32_e32 v8, v8
	v_rcp_f32_e32 v9, v9
	v_pk_mul_f32 v[12:13], v[100:101], v[16:17] op_sel_hi:[1,0]
	v_cvt_pk_bf16_f32 v248, v4, v5
	v_pk_mul_f32 v[6:7], v[12:13], v[6:7]
	v_pk_mul_f32 v[8:9], v[8:9], v[10:11]
	s_nop 0
	v_pk_mul_f32 v[6:7], v[6:7], v[8:9]
	s_waitcnt lgkmcnt(0)
	v_lshlrev_b32_e32 v8, 16, v18
	v_and_b32_e32 v9, 0xffff0000, v18
	v_mul_f32_e32 v5, 0xbfb8aa3b, v8
	v_exp_f32_e32 v10, v5
	v_mul_f32_e32 v5, 0xbfb8aa3b, v9
	v_exp_f32_e32 v11, v5
	v_cvt_pk_bf16_f32 v249, v6, v7
	v_add_f32_e32 v6, 1.0, v10
	v_rcp_f32_e32 v6, v6
	v_add_f32_e32 v7, 1.0, v11
	v_rcp_f32_e32 v7, v7
	v_pk_mul_f32 v[4:5], v[98:99], v[16:17] op_sel_hi:[1,0]
	s_waitcnt vmcnt(3)
	v_pk_mul_f32 v[0:1], v[4:5], v[0:1]
	v_pk_mul_f32 v[4:5], v[6:7], v[8:9]
	v_lshlrev_b32_e32 v6, 16, v19
	v_and_b32_e32 v7, 0xffff0000, v19
	v_mul_f32_e32 v8, 0xbfb8aa3b, v6
	v_mul_f32_e32 v9, 0xbfb8aa3b, v7
	v_exp_f32_e32 v8, v8
	v_exp_f32_e32 v9, v9
	v_pk_mul_f32 v[0:1], v[0:1], v[4:5]
	v_add_f32_e32 v4, 1.0, v8
	v_add_f32_e32 v5, 1.0, v9
	v_rcp_f32_e32 v4, v4
	v_rcp_f32_e32 v5, v5
	v_pk_mul_f32 v[8:9], v[104:105], v[16:17] op_sel_hi:[1,0]
	v_cvt_pk_bf16_f32 v250, v0, v1
	v_pk_mul_f32 v[2:3], v[8:9], v[2:3]
	v_pk_mul_f32 v[4:5], v[4:5], v[6:7]
	s_nop 0
	v_pk_mul_f32 v[2:3], v[2:3], v[4:5]
	s_nop 0
	v_cvt_pk_bf16_f32 v251, v2, v3
	s_nop 1
	v_permlane32_swap_b32_e32 v248, v250
	v_permlane32_swap_b32_e32 v249, v251
	global_store_dwordx4 v[254:255], v[248:251], off offset:1632
	s_branch .LBB0_395
